# GEMM K loops: all 16 LDS-DMA loads per iteration in scalar-base form; second K step's base (ptr + stride) kept in a spare SGPR pair; no VALU address adds left in the loop
# speedup vs baseline: 1.0090x; 1.0009x over previous
.LBB0_118:
	ds_read_b128 v[128:131], v221
	ds_read_b128 v[132:135], v221 offset:1024
	ds_read_b128 v[136:139], v221 offset:2048
	ds_read_b128 v[140:143], v221 offset:3072
	s_add_u32 s8, s6, 0xfff80080
	s_addc_u32 s9, s7, -1
	s_cmp_eq_u32 s53, 28
	s_cselect_b32 s11, s5, s9
	s_cselect_b32 s10, s33, s8
	s_cselect_b32 s9, s43, s52
	s_cselect_b32 s8, s45, s51

	s_add_i32 m0, s58, 0xc000
	ds_read_b128 v[144:147], v222
	ds_read_b128 v[148:151], v222 offset:1024
	ds_read_b128 v[152:155], v222 offset:2048
	ds_read_b128 v[156:159], v222 offset:3072
	ds_read_b128 v[160:163], v222 offset:4096
	ds_read_b128 v[164:167], v222 offset:5120
	ds_read_b128 v[190:193], v222 offset:6144
	ds_read_b128 v[194:197], v222 offset:7168
	global_load_lds_dwordx4 v182, s[6:7]
	s_add_i32 m0, s58, 0xe000
	s_nop 0

	global_load_lds_dwordx4 v184, s[6:7]
	s_waitcnt lgkmcnt(8)
	s_barrier
	s_waitcnt lgkmcnt(0)


	v_mfma_f32_16x16x32_bf16 v[124:127], v[128:131], v[144:147], v[124:127]
	v_mfma_f32_16x16x32_bf16 v[116:119], v[136:139], v[144:147], v[116:119]
	v_mfma_f32_16x16x32_bf16 v[108:111], v[128:131], v[152:155], v[108:111]
	v_mfma_f32_16x16x32_bf16 v[100:103], v[136:139], v[152:155], v[100:103]
	v_mfma_f32_16x16x32_bf16 v[92:95], v[128:131], v[160:163], v[92:95]
	v_mfma_f32_16x16x32_bf16 v[84:87], v[136:139], v[160:163], v[84:87]
	v_mfma_f32_16x16x32_bf16 v[76:79], v[128:131], v[190:193], v[76:79]
	v_mfma_f32_16x16x32_bf16 v[68:71], v[136:139], v[190:193], v[68:71]
	v_mfma_f32_16x16x32_bf16 v[124:127], v[132:135], v[148:151], v[124:127]
	v_mfma_f32_16x16x32_bf16 v[116:119], v[140:143], v[148:151], v[116:119]
	v_mfma_f32_16x16x32_bf16 v[108:111], v[132:135], v[156:159], v[108:111]
	v_mfma_f32_16x16x32_bf16 v[100:103], v[140:143], v[156:159], v[100:103]
	v_mfma_f32_16x16x32_bf16 v[92:95], v[132:135], v[164:167], v[92:95]
	v_mfma_f32_16x16x32_bf16 v[84:87], v[140:143], v[164:167], v[84:87]
	v_mfma_f32_16x16x32_bf16 v[76:79], v[132:135], v[194:197], v[76:79]
	v_mfma_f32_16x16x32_bf16 v[68:71], v[140:143], v[194:197], v[68:71]

	s_barrier
	s_add_i32 s54, s81, s57
	s_add_u32 s66, s8, s20
	s_addc_u32 s67, s9, s21
	s_mov_b32 m0, s54
	ds_read_b128 v[198:201], v223
	ds_read_b128 v[202:205], v223 offset:1024
	ds_read_b128 v[206:209], v223 offset:2048
	ds_read_b128 v[226:229], v223 offset:3072
	global_load_lds_dwordx4 v172, s[8:9]
	s_add_i32 m0, s54, 0x2000
	s_nop 0

	global_load_lds_dwordx4 v174, s[8:9]
	s_barrier
	s_waitcnt lgkmcnt(0)


	v_mfma_f32_16x16x32_bf16 v[120:123], v[198:201], v[144:147], v[120:123]
	v_mfma_f32_16x16x32_bf16 v[112:115], v[206:209], v[144:147], v[112:115]
	v_mfma_f32_16x16x32_bf16 v[104:107], v[198:201], v[152:155], v[104:107]
	v_mfma_f32_16x16x32_bf16 v[96:99], v[206:209], v[152:155], v[96:99]
	v_mfma_f32_16x16x32_bf16 v[88:91], v[198:201], v[160:163], v[88:91]
	v_mfma_f32_16x16x32_bf16 v[80:83], v[206:209], v[160:163], v[80:83]
	v_mfma_f32_16x16x32_bf16 v[72:75], v[198:201], v[190:193], v[72:75]
	v_mfma_f32_16x16x32_bf16 v[64:67], v[206:209], v[190:193], v[64:67]
	v_mfma_f32_16x16x32_bf16 v[120:123], v[202:205], v[148:151], v[120:123]
	v_mfma_f32_16x16x32_bf16 v[112:115], v[226:229], v[148:151], v[112:115]
	v_mfma_f32_16x16x32_bf16 v[104:107], v[202:205], v[156:159], v[104:107]
	v_mfma_f32_16x16x32_bf16 v[96:99], v[226:229], v[156:159], v[96:99]
	v_mfma_f32_16x16x32_bf16 v[88:91], v[202:205], v[164:167], v[88:91]
	v_mfma_f32_16x16x32_bf16 v[80:83], v[226:229], v[164:167], v[80:83]
	v_mfma_f32_16x16x32_bf16 v[72:75], v[202:205], v[194:197], v[72:75]
	v_mfma_f32_16x16x32_bf16 v[64:67], v[226:229], v[194:197], v[64:67]

	s_mov_b32 m0, s58
	s_add_u32 s68, s10, s20
	s_addc_u32 s69, s11, s21
	s_barrier
	ds_read_b128 v[144:147], v222 offset:16384
	ds_read_b128 v[148:151], v222 offset:17408
	ds_read_b128 v[152:155], v222 offset:18432
	ds_read_b128 v[156:159], v222 offset:19456
	ds_read_b128 v[160:163], v222 offset:20480
	ds_read_b128 v[164:167], v222 offset:21504
	ds_read_b128 v[190:193], v222 offset:22528
	ds_read_b128 v[194:197], v222 offset:23552
	global_load_lds_dwordx4 v172, s[10:11]
	s_mov_b32 m0, s59
	s_nop 0

	global_load_lds_dwordx4 v174, s[10:11]
	s_barrier
	s_waitcnt lgkmcnt(0)


	v_mfma_f32_16x16x32_bf16 v[60:63], v[128:131], v[144:147], v[60:63]
	v_mfma_f32_16x16x32_bf16 v[52:55], v[136:139], v[144:147], v[52:55]
	v_mfma_f32_16x16x32_bf16 v[44:47], v[128:131], v[152:155], v[44:47]
	v_mfma_f32_16x16x32_bf16 v[36:39], v[136:139], v[152:155], v[36:39]
	v_mfma_f32_16x16x32_bf16 v[28:31], v[128:131], v[160:163], v[28:31]
	v_mfma_f32_16x16x32_bf16 v[20:23], v[136:139], v[160:163], v[20:23]
	v_mfma_f32_16x16x32_bf16 v[12:15], v[128:131], v[190:193], v[12:15]
	v_mfma_f32_16x16x32_bf16 v[4:7], v[136:139], v[190:193], v[4:7]
	v_mfma_f32_16x16x32_bf16 v[60:63], v[132:135], v[148:151], v[60:63]
	v_mfma_f32_16x16x32_bf16 v[52:55], v[140:143], v[148:151], v[52:55]
	v_mfma_f32_16x16x32_bf16 v[44:47], v[132:135], v[156:159], v[44:47]
	v_mfma_f32_16x16x32_bf16 v[36:39], v[140:143], v[156:159], v[36:39]
	v_mfma_f32_16x16x32_bf16 v[28:31], v[132:135], v[164:167], v[28:31]
	v_mfma_f32_16x16x32_bf16 v[20:23], v[140:143], v[164:167], v[20:23]
	v_mfma_f32_16x16x32_bf16 v[12:15], v[132:135], v[194:197], v[12:15]
	v_mfma_f32_16x16x32_bf16 v[4:7], v[140:143], v[194:197], v[4:7]

	s_barrier
	s_add_u32 s54, s8, 0x80000
	s_addc_u32 s55, s9, 0
	s_add_i32 vcc_lo, s30, s57
	s_mov_b32 m0, vcc_lo
	s_nop 0

	global_load_lds_dwordx4 v172, s[54:55]
	s_add_i32 m0, vcc_lo, 0x2000
	s_nop 0

	global_load_lds_dwordx4 v174, s[54:55]
	s_waitcnt vmcnt(6)
	s_barrier

	v_mfma_f32_16x16x32_bf16 v[56:59], v[198:201], v[144:147], v[56:59]
	v_mfma_f32_16x16x32_bf16 v[48:51], v[206:209], v[144:147], v[48:51]
	v_mfma_f32_16x16x32_bf16 v[40:43], v[198:201], v[152:155], v[40:43]
	v_mfma_f32_16x16x32_bf16 v[32:35], v[206:209], v[152:155], v[32:35]
	v_mfma_f32_16x16x32_bf16 v[24:27], v[198:201], v[160:163], v[24:27]
	v_mfma_f32_16x16x32_bf16 v[16:19], v[206:209], v[160:163], v[16:19]
	v_mfma_f32_16x16x32_bf16 v[8:11], v[198:201], v[190:193], v[8:11]
	v_mfma_f32_16x16x32_bf16 v[0:3], v[206:209], v[190:193], v[0:3]
	v_mfma_f32_16x16x32_bf16 v[56:59], v[202:205], v[148:151], v[56:59]
	v_mfma_f32_16x16x32_bf16 v[48:51], v[226:229], v[148:151], v[48:51]
	v_mfma_f32_16x16x32_bf16 v[40:43], v[202:205], v[156:159], v[40:43]
	v_mfma_f32_16x16x32_bf16 v[32:35], v[226:229], v[156:159], v[32:35]
	v_mfma_f32_16x16x32_bf16 v[24:27], v[202:205], v[164:167], v[24:27]
	v_mfma_f32_16x16x32_bf16 v[16:19], v[226:229], v[164:167], v[16:19]
	v_mfma_f32_16x16x32_bf16 v[8:11], v[202:205], v[194:197], v[8:11]
	v_mfma_f32_16x16x32_bf16 v[0:3], v[226:229], v[194:197], v[0:3]

	s_add_i32 s54, 0, 0x18000
	v_add_u32_e32 v140, s54, v179
	s_barrier
	ds_read_b128 v[128:131], v140
	ds_read_b128 v[132:135], v140 offset:1024
	ds_read_b128 v[136:139], v140 offset:2048
	ds_read_b128 v[140:143], v140 offset:3072
	s_add_u32 s10, s10, 0x80000
	s_addc_u32 s11, s11, 0
	s_mov_b32 m0, s2

	ds_read_b128 v[144:147], v222 offset:32768
	ds_read_b128 v[148:151], v222 offset:33792
	ds_read_b128 v[152:155], v222 offset:34816
	ds_read_b128 v[156:159], v222 offset:35840
	ds_read_b128 v[160:163], v222 offset:36864
	ds_read_b128 v[164:167], v222 offset:37888
	ds_read_b128 v[190:193], v222 offset:38912
	ds_read_b128 v[194:197], v222 offset:39936
	global_load_lds_dwordx4 v172, s[10:11]
	s_mov_b32 m0, s3
	s_nop 0

	global_load_lds_dwordx4 v174, s[10:11]
	s_waitcnt lgkmcnt(8)
	s_barrier
	s_waitcnt lgkmcnt(0)


	v_mfma_f32_16x16x32_bf16 v[124:127], v[128:131], v[144:147], v[124:127]
	v_mfma_f32_16x16x32_bf16 v[116:119], v[136:139], v[144:147], v[116:119]
	v_mfma_f32_16x16x32_bf16 v[108:111], v[128:131], v[152:155], v[108:111]
	v_mfma_f32_16x16x32_bf16 v[100:103], v[136:139], v[152:155], v[100:103]
	v_mfma_f32_16x16x32_bf16 v[92:95], v[128:131], v[160:163], v[92:95]
	v_mfma_f32_16x16x32_bf16 v[84:87], v[136:139], v[160:163], v[84:87]
	v_mfma_f32_16x16x32_bf16 v[76:79], v[128:131], v[190:193], v[76:79]
	v_mfma_f32_16x16x32_bf16 v[68:71], v[136:139], v[190:193], v[68:71]
	v_mfma_f32_16x16x32_bf16 v[124:127], v[132:135], v[148:151], v[124:127]
	v_mfma_f32_16x16x32_bf16 v[116:119], v[140:143], v[148:151], v[116:119]
	v_mfma_f32_16x16x32_bf16 v[108:111], v[132:135], v[156:159], v[108:111]
	v_mfma_f32_16x16x32_bf16 v[100:103], v[140:143], v[156:159], v[100:103]
	v_mfma_f32_16x16x32_bf16 v[92:95], v[132:135], v[164:167], v[92:95]
	v_mfma_f32_16x16x32_bf16 v[84:87], v[140:143], v[164:167], v[84:87]
	v_mfma_f32_16x16x32_bf16 v[76:79], v[132:135], v[194:197], v[76:79]
	v_mfma_f32_16x16x32_bf16 v[68:71], v[140:143], v[194:197], v[68:71]

	s_barrier
	s_add_i32 s10, 0, 0x1c000
	s_add_i32 s11, s54, s57
	v_add_u32_e32 v180, s10, v179

	s_mov_b32 m0, s11
	ds_read_b128 v[198:201], v180
	ds_read_b128 v[202:205], v180 offset:1024
	ds_read_b128 v[206:209], v180 offset:2048
	ds_read_b128 v[226:229], v180 offset:3072
	global_load_lds_dwordx4 v172, s[66:67]
	s_add_i32 m0, s11, 0x2000
	s_nop 0

	global_load_lds_dwordx4 v174, s[66:67]
	s_barrier
	s_waitcnt lgkmcnt(0)


	v_mfma_f32_16x16x32_bf16 v[120:123], v[198:201], v[144:147], v[120:123]
	v_mfma_f32_16x16x32_bf16 v[112:115], v[206:209], v[144:147], v[112:115]
	v_mfma_f32_16x16x32_bf16 v[104:107], v[198:201], v[152:155], v[104:107]
	v_mfma_f32_16x16x32_bf16 v[96:99], v[206:209], v[152:155], v[96:99]
	v_mfma_f32_16x16x32_bf16 v[88:91], v[198:201], v[160:163], v[88:91]
	v_mfma_f32_16x16x32_bf16 v[80:83], v[206:209], v[160:163], v[80:83]
	v_mfma_f32_16x16x32_bf16 v[72:75], v[198:201], v[190:193], v[72:75]
	v_mfma_f32_16x16x32_bf16 v[64:67], v[206:209], v[190:193], v[64:67]
	v_mfma_f32_16x16x32_bf16 v[120:123], v[202:205], v[148:151], v[120:123]
	v_mfma_f32_16x16x32_bf16 v[112:115], v[226:229], v[148:151], v[112:115]
	v_mfma_f32_16x16x32_bf16 v[104:107], v[202:205], v[156:159], v[104:107]
	v_mfma_f32_16x16x32_bf16 v[96:99], v[226:229], v[156:159], v[96:99]
	v_mfma_f32_16x16x32_bf16 v[88:91], v[202:205], v[164:167], v[88:91]
	v_mfma_f32_16x16x32_bf16 v[80:83], v[226:229], v[164:167], v[80:83]
	v_mfma_f32_16x16x32_bf16 v[72:75], v[202:205], v[194:197], v[72:75]
	v_mfma_f32_16x16x32_bf16 v[64:67], v[226:229], v[194:197], v[64:67]

	s_mov_b32 m0, s96

	s_barrier
	ds_read_b128 v[144:147], v222 offset:49152
	ds_read_b128 v[148:151], v222 offset:50176
	ds_read_b128 v[152:155], v222 offset:51200
	ds_read_b128 v[156:159], v222 offset:52224
	ds_read_b128 v[160:163], v222 offset:53248
	ds_read_b128 v[164:167], v222 offset:54272
	ds_read_b128 v[190:193], v222 offset:55296
	ds_read_b128 v[194:197], v222 offset:56320
	global_load_lds_dwordx4 v172, s[68:69]
	s_mov_b32 m0, s97
	s_nop 0

	global_load_lds_dwordx4 v174, s[68:69]
	s_barrier
	s_waitcnt lgkmcnt(0)


	v_mfma_f32_16x16x32_bf16 v[60:63], v[128:131], v[144:147], v[60:63]
	v_mfma_f32_16x16x32_bf16 v[52:55], v[136:139], v[144:147], v[52:55]
	v_mfma_f32_16x16x32_bf16 v[44:47], v[128:131], v[152:155], v[44:47]
	v_mfma_f32_16x16x32_bf16 v[36:39], v[136:139], v[152:155], v[36:39]
	v_mfma_f32_16x16x32_bf16 v[28:31], v[128:131], v[160:163], v[28:31]
	v_mfma_f32_16x16x32_bf16 v[20:23], v[136:139], v[160:163], v[20:23]
	v_mfma_f32_16x16x32_bf16 v[12:15], v[128:131], v[190:193], v[12:15]
	v_mfma_f32_16x16x32_bf16 v[4:7], v[136:139], v[190:193], v[4:7]
	v_mfma_f32_16x16x32_bf16 v[60:63], v[132:135], v[148:151], v[60:63]
	v_mfma_f32_16x16x32_bf16 v[52:55], v[140:143], v[148:151], v[52:55]
	v_mfma_f32_16x16x32_bf16 v[44:47], v[132:135], v[156:159], v[44:47]
	v_mfma_f32_16x16x32_bf16 v[36:39], v[140:143], v[156:159], v[36:39]
	v_mfma_f32_16x16x32_bf16 v[28:31], v[132:135], v[164:167], v[28:31]
	v_mfma_f32_16x16x32_bf16 v[20:23], v[140:143], v[164:167], v[20:23]
	v_mfma_f32_16x16x32_bf16 v[12:15], v[132:135], v[194:197], v[12:15]
	v_mfma_f32_16x16x32_bf16 v[4:7], v[140:143], v[194:197], v[4:7]

	s_barrier
	s_add_u32 s8, s8, 0x80080
	s_addc_u32 s9, s9, 0
	s_add_i32 s10, s10, s57
	s_mov_b32 m0, s10
	s_nop 0

	global_load_lds_dwordx4 v172, s[8:9]
	s_add_i32 m0, s10, 0x2000
	s_nop 0

	global_load_lds_dwordx4 v174, s[8:9]
	s_waitcnt vmcnt(6)
	s_barrier

	v_mfma_f32_16x16x32_bf16 v[56:59], v[198:201], v[144:147], v[56:59]
	v_mfma_f32_16x16x32_bf16 v[48:51], v[206:209], v[144:147], v[48:51]
	v_mfma_f32_16x16x32_bf16 v[40:43], v[198:201], v[152:155], v[40:43]
	v_mfma_f32_16x16x32_bf16 v[32:35], v[206:209], v[152:155], v[32:35]
	v_mfma_f32_16x16x32_bf16 v[24:27], v[198:201], v[160:163], v[24:27]
	v_mfma_f32_16x16x32_bf16 v[16:19], v[206:209], v[160:163], v[16:19]
	v_mfma_f32_16x16x32_bf16 v[8:11], v[198:201], v[190:193], v[8:11]
	v_mfma_f32_16x16x32_bf16 v[0:3], v[206:209], v[190:193], v[0:3]
	v_mfma_f32_16x16x32_bf16 v[56:59], v[202:205], v[148:151], v[56:59]
	v_mfma_f32_16x16x32_bf16 v[48:51], v[226:229], v[148:151], v[48:51]
	v_mfma_f32_16x16x32_bf16 v[40:43], v[202:205], v[156:159], v[40:43]
	v_mfma_f32_16x16x32_bf16 v[32:35], v[226:229], v[156:159], v[32:35]
	v_mfma_f32_16x16x32_bf16 v[24:27], v[202:205], v[164:167], v[24:27]
	v_mfma_f32_16x16x32_bf16 v[16:19], v[226:229], v[164:167], v[16:19]
	v_mfma_f32_16x16x32_bf16 v[8:11], v[202:205], v[194:197], v[8:11]
	v_mfma_f32_16x16x32_bf16 v[0:3], v[226:229], v[194:197], v[0:3]

	s_add_i32 s53, s53, 2
	s_add_u32 s6, s6, 0x100
	s_addc_u32 s7, s7, 0
	s_add_u32 s51, s51, 0x100
	s_addc_u32 s52, s52, 0
	s_cmp_gt_u32 s53, 29
	s_barrier
	s_cbranch_scc0 .LBB0_118
	v_mov_b32_e32 v142, v210
	v_mov_b32_e32 v143, v169
	s_lshl_b32 s33, s4, 8
	s_add_i32 s33, s33, s34
	v_lshl_add_u32 v133, v142, 4, v143
	v_ashrrev_i32_e32 v198, 2, v133
	v_and_b32_e32 v192, 3, v143
	v_and_b32_e32 v128, -4, v133
	s_cmp_gt_i32 s4, 30
	v_lshl_add_u32 v226, v192, 6, v128
	v_add_u32_e32 v190, s33, v198
	s_cselect_b64 s[52:53], -1, 0
	s_cmp_gt_i32 s50, 8
	s_mov_b64 s[4:5], -1
	s_cbranch_scc0 .LBB0_419
	s_cmp_lg_u32 s50, 9
	s_cbranch_scc0 .LBB0_225
	s_cmp_gt_u32 s50, 25
	s_cbranch_scc0 .LBB0_127
	v_mul_f32_e32 v130, 0xbfb8aa3b, v120
	v_mul_f32_e32 v131, 0xbfb8aa3b, v121
	v_mul_f32_e32 v132, 0xbfb8aa3b, v122
	v_mul_f32_e32 v134, 0xbfb8aa3b, v123
	v_mul_f32_e32 v135, 0xbfb8aa3b, v112
	v_mul_f32_e32 v136, 0xbfb8aa3b, v113
	v_mul_f32_e32 v137, 0xbfb8aa3b, v114
	v_mul_f32_e32 v138, 0xbfb8aa3b, v115
	v_mul_f32_e32 v139, 0xbfb8aa3b, v104
	v_mul_f32_e32 v140, 0xbfb8aa3b, v105
	v_mul_f32_e32 v141, 0xbfb8aa3b, v106
	v_mul_f32_e32 v144, 0xbfb8aa3b, v107
	v_mul_f32_e32 v145, 0xbfb8aa3b, v96
	v_mul_f32_e32 v146, 0xbfb8aa3b, v97
	v_mul_f32_e32 v147, 0xbfb8aa3b, v98
	v_mul_f32_e32 v148, 0xbfb8aa3b, v99
	v_mul_f32_e32 v149, 0xbfb8aa3b, v88
	v_mul_f32_e32 v150, 0xbfb8aa3b, v89
	v_mul_f32_e32 v151, 0xbfb8aa3b, v90
	v_mul_f32_e32 v152, 0xbfb8aa3b, v91
	v_mul_f32_e32 v153, 0xbfb8aa3b, v80
	v_mul_f32_e32 v154, 0xbfb8aa3b, v81
	v_mul_f32_e32 v155, 0xbfb8aa3b, v82
	v_mul_f32_e32 v180, 0xbfb8aa3b, v83
	v_mul_f32_e32 v206, 0xbfb8aa3b, v72
	v_mul_f32_e32 v207, 0xbfb8aa3b, v73
	v_mul_f32_e32 v208, 0xbfb8aa3b, v74
	v_mul_f32_e32 v209, 0xbfb8aa3b, v75
	v_mul_f32_e32 v227, 0xbfb8aa3b, v64
	v_mul_f32_e32 v228, 0xbfb8aa3b, v65
	v_mul_f32_e32 v229, 0xbfb8aa3b, v66
	v_mul_f32_e32 v230, 0xbfb8aa3b, v67
	v_exp_f32_e32 v205, v130
	v_exp_f32_e32 v204, v131
	v_exp_f32_e32 v203, v132
	v_exp_f32_e32 v202, v134
	v_exp_f32_e32 v200, v135
	v_exp_f32_e32 v199, v136
	v_exp_f32_e32 v197, v137
	v_exp_f32_e32 v196, v138
	v_exp_f32_e32 v195, v139
	v_exp_f32_e32 v194, v140
	v_exp_f32_e32 v193, v141
	v_exp_f32_e32 v167, v144
	v_exp_f32_e32 v166, v145
	v_exp_f32_e32 v165, v146
	v_exp_f32_e32 v164, v147
	v_exp_f32_e32 v163, v148
	v_exp_f32_e32 v162, v149
	v_exp_f32_e32 v161, v150
	v_exp_f32_e32 v160, v151
	v_exp_f32_e32 v159, v152
	v_exp_f32_e32 v158, v153
	v_exp_f32_e32 v157, v154
	v_exp_f32_e32 v156, v155
	v_exp_f32_e32 v155, v180
	v_exp_f32_e32 v154, v206
	v_exp_f32_e32 v153, v207
	v_exp_f32_e32 v152, v208
	v_exp_f32_e32 v151, v209
	v_exp_f32_e32 v150, v227
	v_exp_f32_e32 v149, v228
	v_exp_f32_e32 v148, v229
	v_exp_f32_e32 v147, v230
	v_ashrrev_i32_e32 v191, 31, v190
	s_cmp_lt_u32 s50, 42
	v_lshlrev_b32_e32 v201, 2, v192
	v_lshlrev_b64 v[128:129], 12, v[190:191]
	v_mul_f32_e32 v146, 0xbfb8aa3b, v56
	v_mul_f32_e32 v145, 0xbfb8aa3b, v57
	v_mul_f32_e32 v144, 0xbfb8aa3b, v58
	v_mul_f32_e32 v141, 0xbfb8aa3b, v59
	v_mul_f32_e32 v140, 0xbfb8aa3b, v48
	v_mul_f32_e32 v139, 0xbfb8aa3b, v49
	v_mul_f32_e32 v138, 0xbfb8aa3b, v50
	v_mul_f32_e32 v137, 0xbfb8aa3b, v51
	v_mul_f32_e32 v136, 0xbfb8aa3b, v40
	v_mul_f32_e32 v135, 0xbfb8aa3b, v41
	v_mul_f32_e32 v134, 0xbfb8aa3b, v42
	v_mul_f32_e32 v132, 0xbfb8aa3b, v43
	s_cbranch_scc1 .LBB0_124
	v_mul_f32_e32 v130, 0xbfb8aa3b, v124
	v_mul_f32_e32 v131, 0xbfb8aa3b, v125
	v_mul_f32_e32 v206, 0xbfb8aa3b, v126
	v_mul_f32_e32 v207, 0xbfb8aa3b, v127
	v_exp_f32_e32 v130, v130
	v_exp_f32_e32 v131, v131
	v_exp_f32_e32 v206, v206
	v_exp_f32_e32 v207, v207
	v_add_f32_e32 v130, 1.0, v130
	v_add_f32_e32 v131, 1.0, v131
	v_add_f32_e32 v206, 1.0, v206
	v_add_f32_e32 v207, 1.0, v207
	v_rcp_f32_e32 v130, v130
	v_rcp_f32_e32 v131, v131
	v_rcp_f32_e32 v206, v206
	v_rcp_f32_e32 v207, v207
	s_lshl_b32 s4, s50, 8
	v_cvt_pk_bf16_f32 v130, v130, v131
	s_add_i32 s4, s28, s4
	v_cvt_pk_bf16_f32 v131, v206, v207
	ds_bpermute_b32 v206, v226, v130
	ds_bpermute_b32 v207, v226, v131
	v_or_b32_e32 v180, s4, v201
	v_lshl_add_u64 v[130:131], s[40:41], 0, v[128:129]
	v_lshlrev_b64 v[208:209], 1, v[180:181]
	v_lshl_add_u64 v[130:131], v[130:131], 0, v[208:209]
	s_waitcnt lgkmcnt(0)
	global_store_dwordx2 v[130:131], v[206:207], off
	v_mul_f32_e32 v180, 0xbfb8aa3b, v116
	v_mul_f32_e32 v206, 0xbfb8aa3b, v117
	v_mul_f32_e32 v207, 0xbfb8aa3b, v118
	v_mul_f32_e32 v208, 0xbfb8aa3b, v119
	v_exp_f32_e32 v180, v180
	v_exp_f32_e32 v206, v206
	v_exp_f32_e32 v207, v207
	v_exp_f32_e32 v208, v208
	v_add_f32_e32 v180, 1.0, v180
	v_add_f32_e32 v206, 1.0, v206
	v_add_f32_e32 v207, 1.0, v207
	v_add_f32_e32 v208, 1.0, v208
	v_rcp_f32_e32 v180, v180
	v_rcp_f32_e32 v206, v206
	v_rcp_f32_e32 v207, v207
	v_rcp_f32_e32 v208, v208
	s_mov_b64 s[4:5], 0x10000
	v_cvt_pk_bf16_f32 v180, v180, v206
	ds_bpermute_b32 v206, v226, v180
	v_cvt_pk_bf16_f32 v207, v207, v208
	ds_bpermute_b32 v207, v226, v207
	v_add_f32_e32 v180, 1.0, v205
	v_add_f32_e32 v208, 1.0, v202
	v_rcp_f32_e32 v180, v180
	v_rcp_f32_e32 v208, v208
	s_waitcnt lgkmcnt(0)
	global_store_dwordx2 v[130:131], v[206:207], off offset:32
	v_add_f32_e32 v206, 1.0, v204
	v_add_f32_e32 v207, 1.0, v203
	v_rcp_f32_e32 v206, v206
	v_rcp_f32_e32 v207, v207
	v_mul_f32_e32 v227, 0xbfb8aa3b, v103
	v_exp_f32_e32 v227, v227
	v_cvt_pk_bf16_f32 v180, v180, v206
	v_cvt_pk_bf16_f32 v207, v207, v208
	ds_bpermute_b32 v206, v226, v180
	ds_bpermute_b32 v207, v226, v207
	v_add_f32_e32 v180, 1.0, v200
	v_add_f32_e32 v208, 1.0, v196
	v_rcp_f32_e32 v180, v180
	v_rcp_f32_e32 v208, v208
	s_waitcnt lgkmcnt(0)
	global_store_dwordx2 v[130:131], v[206:207], off offset:256
	v_add_f32_e32 v206, 1.0, v199
	v_add_f32_e32 v207, 1.0, v197
	v_rcp_f32_e32 v206, v206
	v_rcp_f32_e32 v207, v207
	v_add_f32_e32 v227, 1.0, v227
	v_rcp_f32_e32 v227, v227
	v_cvt_pk_bf16_f32 v180, v180, v206
	v_cvt_pk_bf16_f32 v207, v207, v208
	ds_bpermute_b32 v206, v226, v180
	ds_bpermute_b32 v207, v226, v207
	v_mul_f32_e32 v180, 0xbfb8aa3b, v108
	v_mul_f32_e32 v208, 0xbfb8aa3b, v111
	v_exp_f32_e32 v180, v180
	v_exp_f32_e32 v208, v208
	s_waitcnt lgkmcnt(0)
	global_store_dwordx2 v[130:131], v[206:207], off offset:288
	v_mul_f32_e32 v206, 0xbfb8aa3b, v109
	v_mul_f32_e32 v207, 0xbfb8aa3b, v110
	v_exp_f32_e32 v206, v206
	v_exp_f32_e32 v207, v207
	v_add_f32_e32 v180, 1.0, v180
	v_add_f32_e32 v208, 1.0, v208
	v_add_f32_e32 v206, 1.0, v206
	v_add_f32_e32 v207, 1.0, v207
	v_rcp_f32_e32 v180, v180
	v_rcp_f32_e32 v206, v206
	v_rcp_f32_e32 v207, v207
	v_rcp_f32_e32 v208, v208
	v_cvt_pk_bf16_f32 v180, v180, v206
	ds_bpermute_b32 v206, v226, v180
	v_cvt_pk_bf16_f32 v207, v207, v208
	ds_bpermute_b32 v207, v226, v207
	v_lshl_add_u64 v[208:209], v[130:131], 0, s[4:5]
	s_mov_b32 s4, 0x10000
	v_add_co_u32_e32 v228, vcc, s4, v130
	v_mul_f32_e32 v180, 0xbfb8aa3b, v100
	s_nop 0
	v_addc_co_u32_e32 v229, vcc, 0, v131, vcc
	s_waitcnt lgkmcnt(0)
	global_store_dwordx2 v[228:229], v[206:207], off
	v_mul_f32_e32 v206, 0xbfb8aa3b, v101
	v_mul_f32_e32 v207, 0xbfb8aa3b, v102
	v_exp_f32_e32 v180, v180
	v_exp_f32_e32 v206, v206
	v_exp_f32_e32 v207, v207
	s_mov_b64 s[4:5], 0x20000
	v_add_f32_e32 v180, 1.0, v180
	v_add_f32_e32 v206, 1.0, v206
	v_add_f32_e32 v207, 1.0, v207
	v_rcp_f32_e32 v180, v180
	v_rcp_f32_e32 v206, v206
	v_rcp_f32_e32 v207, v207
	v_cvt_pk_bf16_f32 v180, v180, v206
	v_cvt_pk_bf16_f32 v207, v207, v227
	ds_bpermute_b32 v206, v226, v180
	ds_bpermute_b32 v207, v226, v207
	v_add_f32_e32 v180, 1.0, v195
	v_add_f32_e32 v227, 1.0, v167
	v_rcp_f32_e32 v180, v180
	v_rcp_f32_e32 v227, v227
	s_waitcnt lgkmcnt(0)
	global_store_dwordx2 v[208:209], v[206:207], off offset:32
	v_add_f32_e32 v206, 1.0, v194
	v_add_f32_e32 v207, 1.0, v193
	v_rcp_f32_e32 v206, v206
	v_rcp_f32_e32 v207, v207
	v_cvt_pk_bf16_f32 v180, v180, v206
	v_cvt_pk_bf16_f32 v207, v207, v227
	ds_bpermute_b32 v206, v226, v180
	ds_bpermute_b32 v207, v226, v207
	v_add_f32_e32 v180, 1.0, v166
	v_add_f32_e32 v227, 1.0, v163
	v_rcp_f32_e32 v180, v180
	v_rcp_f32_e32 v227, v227
	s_waitcnt lgkmcnt(0)
	global_store_dwordx2 v[208:209], v[206:207], off offset:256
	v_add_f32_e32 v206, 1.0, v165
	v_add_f32_e32 v207, 1.0, v164
	v_rcp_f32_e32 v206, v206
	v_rcp_f32_e32 v207, v207
	v_cvt_pk_bf16_f32 v180, v180, v206
	v_cvt_pk_bf16_f32 v207, v207, v227
	ds_bpermute_b32 v206, v226, v180
	ds_bpermute_b32 v207, v226, v207
	v_mul_f32_e32 v180, 0xbfb8aa3b, v92
	v_exp_f32_e32 v180, v180
	v_mul_f32_e32 v227, 0xbfb8aa3b, v87
	v_exp_f32_e32 v227, v227
	s_waitcnt lgkmcnt(0)
	global_store_dwordx2 v[208:209], v[206:207], off offset:288
	v_mul_f32_e32 v206, 0xbfb8aa3b, v93
	v_mul_f32_e32 v207, 0xbfb8aa3b, v94
	v_mul_f32_e32 v208, 0xbfb8aa3b, v95
	v_exp_f32_e32 v206, v206
	v_exp_f32_e32 v207, v207
	v_exp_f32_e32 v208, v208
	v_add_f32_e32 v180, 1.0, v180
	v_add_f32_e32 v206, 1.0, v206
	v_add_f32_e32 v207, 1.0, v207
	v_add_f32_e32 v208, 1.0, v208
	v_rcp_f32_e32 v180, v180
	v_rcp_f32_e32 v206, v206
	v_rcp_f32_e32 v207, v207
	v_rcp_f32_e32 v208, v208
	v_add_f32_e32 v227, 1.0, v227
	v_cvt_pk_bf16_f32 v180, v180, v206
	ds_bpermute_b32 v206, v226, v180
	v_cvt_pk_bf16_f32 v207, v207, v208
	ds_bpermute_b32 v207, v226, v207
	v_lshl_add_u64 v[208:209], v[130:131], 0, s[4:5]
	s_mov_b32 s4, 0x20000
	v_add_co_u32_e32 v228, vcc, s4, v130
	v_mul_f32_e32 v180, 0xbfb8aa3b, v84
	s_nop 0
	v_addc_co_u32_e32 v229, vcc, 0, v131, vcc
	s_waitcnt lgkmcnt(0)
	global_store_dwordx2 v[228:229], v[206:207], off
	v_mul_f32_e32 v206, 0xbfb8aa3b, v85
	v_mul_f32_e32 v207, 0xbfb8aa3b, v86
	v_exp_f32_e32 v180, v180
	v_exp_f32_e32 v206, v206
	v_exp_f32_e32 v207, v207
	v_rcp_f32_e32 v227, v227
	v_add_f32_e32 v180, 1.0, v180
	v_add_f32_e32 v206, 1.0, v206
	v_add_f32_e32 v207, 1.0, v207
	v_rcp_f32_e32 v180, v180
	v_rcp_f32_e32 v206, v206
	v_rcp_f32_e32 v207, v207
	s_mov_b64 s[4:5], 0x30000
	v_cvt_pk_bf16_f32 v180, v180, v206
	v_cvt_pk_bf16_f32 v207, v207, v227
	ds_bpermute_b32 v206, v226, v180
	ds_bpermute_b32 v207, v226, v207
	v_add_f32_e32 v180, 1.0, v162
	v_add_f32_e32 v227, 1.0, v159
	v_rcp_f32_e32 v180, v180
	v_rcp_f32_e32 v227, v227
	s_waitcnt lgkmcnt(0)
	global_store_dwordx2 v[208:209], v[206:207], off offset:32
	v_add_f32_e32 v206, 1.0, v161
	v_add_f32_e32 v207, 1.0, v160
	v_rcp_f32_e32 v206, v206
	v_rcp_f32_e32 v207, v207
	v_cvt_pk_bf16_f32 v180, v180, v206
	v_cvt_pk_bf16_f32 v207, v207, v227
	ds_bpermute_b32 v206, v226, v180
	ds_bpermute_b32 v207, v226, v207
	v_add_f32_e32 v180, 1.0, v158
	v_add_f32_e32 v227, 1.0, v155
	v_rcp_f32_e32 v180, v180
	v_rcp_f32_e32 v227, v227
	s_waitcnt lgkmcnt(0)
	global_store_dwordx2 v[208:209], v[206:207], off offset:256
	v_add_f32_e32 v206, 1.0, v157
	v_add_f32_e32 v207, 1.0, v156
	v_rcp_f32_e32 v206, v206
	v_rcp_f32_e32 v207, v207
	v_cvt_pk_bf16_f32 v180, v180, v206
	v_cvt_pk_bf16_f32 v207, v207, v227
	ds_bpermute_b32 v206, v226, v180
	ds_bpermute_b32 v207, v226, v207
	v_mul_f32_e32 v180, 0xbfb8aa3b, v76
	v_exp_f32_e32 v180, v180
	v_mul_f32_e32 v227, 0xbfb8aa3b, v71
	v_exp_f32_e32 v227, v227
	s_waitcnt lgkmcnt(0)
	global_store_dwordx2 v[208:209], v[206:207], off offset:288
	v_mul_f32_e32 v206, 0xbfb8aa3b, v77
	v_mul_f32_e32 v207, 0xbfb8aa3b, v78
	v_mul_f32_e32 v208, 0xbfb8aa3b, v79
	v_exp_f32_e32 v206, v206
	v_exp_f32_e32 v207, v207
	v_exp_f32_e32 v208, v208
	v_add_f32_e32 v180, 1.0, v180
	v_add_f32_e32 v206, 1.0, v206
	v_add_f32_e32 v207, 1.0, v207
	v_add_f32_e32 v208, 1.0, v208
	v_rcp_f32_e32 v180, v180
	v_rcp_f32_e32 v206, v206
	v_rcp_f32_e32 v207, v207
	v_rcp_f32_e32 v208, v208
	v_add_f32_e32 v227, 1.0, v227
	v_cvt_pk_bf16_f32 v180, v180, v206
	ds_bpermute_b32 v206, v226, v180
	v_cvt_pk_bf16_f32 v207, v207, v208
	ds_bpermute_b32 v207, v226, v207
	v_lshl_add_u64 v[208:209], v[130:131], 0, s[4:5]
	s_mov_b32 s4, 0x30000
	v_add_co_u32_e32 v228, vcc, s4, v130
	v_mul_f32_e32 v180, 0xbfb8aa3b, v68
	s_nop 0
	v_addc_co_u32_e32 v229, vcc, 0, v131, vcc
	s_waitcnt lgkmcnt(0)
	global_store_dwordx2 v[228:229], v[206:207], off
	v_mul_f32_e32 v206, 0xbfb8aa3b, v69
	v_mul_f32_e32 v207, 0xbfb8aa3b, v70
	v_exp_f32_e32 v180, v180
	v_exp_f32_e32 v206, v206
	v_exp_f32_e32 v207, v207
	v_rcp_f32_e32 v227, v227
	v_add_f32_e32 v180, 1.0, v180
	v_add_f32_e32 v206, 1.0, v206
	v_add_f32_e32 v207, 1.0, v207
	v_rcp_f32_e32 v180, v180
	v_rcp_f32_e32 v206, v206
	v_rcp_f32_e32 v207, v207
	s_mov_b64 s[4:5], 0x80000
	v_cvt_pk_bf16_f32 v180, v180, v206
	v_cvt_pk_bf16_f32 v207, v207, v227
	ds_bpermute_b32 v206, v226, v180
	ds_bpermute_b32 v207, v226, v207
	v_add_f32_e32 v180, 1.0, v154
	v_add_f32_e32 v227, 1.0, v151
	v_rcp_f32_e32 v180, v180
	v_rcp_f32_e32 v227, v227
	s_waitcnt lgkmcnt(0)
	global_store_dwordx2 v[208:209], v[206:207], off offset:32
	v_add_f32_e32 v206, 1.0, v153
	v_add_f32_e32 v207, 1.0, v152
	v_rcp_f32_e32 v206, v206
	v_rcp_f32_e32 v207, v207
	v_cvt_pk_bf16_f32 v180, v180, v206
	v_cvt_pk_bf16_f32 v207, v207, v227
	ds_bpermute_b32 v206, v226, v180
	ds_bpermute_b32 v207, v226, v207
	v_add_f32_e32 v180, 1.0, v150
	v_add_f32_e32 v227, 1.0, v147
	v_rcp_f32_e32 v180, v180
	v_rcp_f32_e32 v227, v227
	s_waitcnt lgkmcnt(0)
	global_store_dwordx2 v[208:209], v[206:207], off offset:256
	v_add_f32_e32 v206, 1.0, v149
	v_add_f32_e32 v207, 1.0, v148
	v_rcp_f32_e32 v206, v206
	v_rcp_f32_e32 v207, v207
	v_cvt_pk_bf16_f32 v180, v180, v206
	v_cvt_pk_bf16_f32 v207, v207, v227
	ds_bpermute_b32 v206, v226, v180
	ds_bpermute_b32 v207, v226, v207
	v_mul_f32_e32 v180, 0xbfb8aa3b, v60
	v_exp_f32_e32 v180, v180
	v_mul_f32_e32 v227, 0xbfb8aa3b, v55
	v_exp_f32_e32 v227, v227
	s_waitcnt lgkmcnt(0)
	global_store_dwordx2 v[208:209], v[206:207], off offset:288
	v_mul_f32_e32 v206, 0xbfb8aa3b, v61
	v_mul_f32_e32 v207, 0xbfb8aa3b, v62
	v_mul_f32_e32 v208, 0xbfb8aa3b, v63
	v_exp_f32_e32 v206, v206
	v_exp_f32_e32 v207, v207
	v_exp_f32_e32 v208, v208
	v_add_f32_e32 v180, 1.0, v180
	v_add_f32_e32 v206, 1.0, v206
	v_add_f32_e32 v207, 1.0, v207
	v_add_f32_e32 v208, 1.0, v208
	v_rcp_f32_e32 v180, v180
	v_rcp_f32_e32 v206, v206
	v_rcp_f32_e32 v207, v207
	v_rcp_f32_e32 v208, v208
	v_add_f32_e32 v227, 1.0, v227
	v_cvt_pk_bf16_f32 v180, v180, v206
	ds_bpermute_b32 v206, v226, v180
	v_cvt_pk_bf16_f32 v207, v207, v208
	ds_bpermute_b32 v207, v226, v207
	v_lshl_add_u64 v[208:209], v[130:131], 0, s[4:5]
	s_mov_b32 s4, 0x80000
	v_add_co_u32_e32 v228, vcc, s4, v130
	v_mul_f32_e32 v180, 0xbfb8aa3b, v52
	s_nop 0
	v_addc_co_u32_e32 v229, vcc, 0, v131, vcc
	s_waitcnt lgkmcnt(0)
	global_store_dwordx2 v[228:229], v[206:207], off
	v_mul_f32_e32 v206, 0xbfb8aa3b, v53
	v_mul_f32_e32 v207, 0xbfb8aa3b, v54
	v_exp_f32_e32 v180, v180
	v_exp_f32_e32 v206, v206
	v_exp_f32_e32 v207, v207
	v_rcp_f32_e32 v227, v227
	v_add_f32_e32 v180, 1.0, v180
	v_add_f32_e32 v206, 1.0, v206
	v_add_f32_e32 v207, 1.0, v207
	v_rcp_f32_e32 v180, v180
	v_rcp_f32_e32 v206, v206
	v_rcp_f32_e32 v207, v207
	s_mov_b64 s[4:5], 0x90000
	v_cvt_pk_bf16_f32 v180, v180, v206
	v_cvt_pk_bf16_f32 v207, v207, v227
	ds_bpermute_b32 v206, v226, v180
	ds_bpermute_b32 v207, v226, v207
	v_exp_f32_e32 v180, v146
	v_exp_f32_e32 v227, v141
	s_waitcnt lgkmcnt(0)
	global_store_dwordx2 v[208:209], v[206:207], off offset:32
	v_exp_f32_e32 v206, v145
	v_exp_f32_e32 v207, v144
	v_add_f32_e32 v180, 1.0, v180
	v_add_f32_e32 v227, 1.0, v227
	v_add_f32_e32 v206, 1.0, v206
	v_add_f32_e32 v207, 1.0, v207
	v_rcp_f32_e32 v180, v180
	v_rcp_f32_e32 v206, v206
	v_rcp_f32_e32 v207, v207
	v_rcp_f32_e32 v227, v227
	v_cvt_pk_bf16_f32 v180, v180, v206
	ds_bpermute_b32 v206, v226, v180
	v_cvt_pk_bf16_f32 v207, v207, v227
	ds_bpermute_b32 v207, v226, v207
	v_exp_f32_e32 v180, v140
	v_exp_f32_e32 v227, v137
	s_waitcnt lgkmcnt(0)
	global_store_dwordx2 v[208:209], v[206:207], off offset:256
	v_exp_f32_e32 v206, v139
	v_exp_f32_e32 v207, v138
	v_add_f32_e32 v180, 1.0, v180
	v_add_f32_e32 v227, 1.0, v227
	v_add_f32_e32 v206, 1.0, v206
	v_add_f32_e32 v207, 1.0, v207
	v_rcp_f32_e32 v180, v180
	v_rcp_f32_e32 v206, v206
	v_rcp_f32_e32 v207, v207
	v_rcp_f32_e32 v227, v227
	v_cvt_pk_bf16_f32 v180, v180, v206
	ds_bpermute_b32 v206, v226, v180
	v_cvt_pk_bf16_f32 v207, v207, v227
	ds_bpermute_b32 v207, v226, v207
	v_mul_f32_e32 v180, 0xbfb8aa3b, v44
	v_exp_f32_e32 v180, v180
	v_mul_f32_e32 v227, 0xbfb8aa3b, v39
	v_exp_f32_e32 v227, v227
	s_waitcnt lgkmcnt(0)
	global_store_dwordx2 v[208:209], v[206:207], off offset:288
	v_mul_f32_e32 v206, 0xbfb8aa3b, v45
	v_mul_f32_e32 v207, 0xbfb8aa3b, v46
	v_mul_f32_e32 v208, 0xbfb8aa3b, v47
	v_exp_f32_e32 v206, v206
	v_exp_f32_e32 v207, v207
	v_exp_f32_e32 v208, v208
	v_add_f32_e32 v180, 1.0, v180
	v_add_f32_e32 v206, 1.0, v206
	v_add_f32_e32 v207, 1.0, v207
	v_add_f32_e32 v208, 1.0, v208
	v_rcp_f32_e32 v180, v180
	v_rcp_f32_e32 v206, v206
	v_rcp_f32_e32 v207, v207
	v_rcp_f32_e32 v208, v208
	v_add_f32_e32 v227, 1.0, v227
	v_cvt_pk_bf16_f32 v180, v180, v206
	ds_bpermute_b32 v206, v226, v180
	v_cvt_pk_bf16_f32 v207, v207, v208
	ds_bpermute_b32 v207, v226, v207
	v_lshl_add_u64 v[208:209], v[130:131], 0, s[4:5]
	s_mov_b32 s4, 0x90000
	v_add_co_u32_e32 v228, vcc, s4, v130
	v_mul_f32_e32 v180, 0xbfb8aa3b, v36
	s_nop 0
	v_addc_co_u32_e32 v229, vcc, 0, v131, vcc
	s_waitcnt lgkmcnt(0)
	global_store_dwordx2 v[228:229], v[206:207], off
	v_mul_f32_e32 v206, 0xbfb8aa3b, v37
	v_mul_f32_e32 v207, 0xbfb8aa3b, v38
	v_exp_f32_e32 v180, v180
	v_exp_f32_e32 v206, v206
	v_exp_f32_e32 v207, v207
	v_rcp_f32_e32 v227, v227
	v_add_f32_e32 v180, 1.0, v180
	v_add_f32_e32 v206, 1.0, v206
	v_add_f32_e32 v207, 1.0, v207
	v_rcp_f32_e32 v180, v180
	v_rcp_f32_e32 v206, v206
	v_rcp_f32_e32 v207, v207
	s_mov_b64 s[4:5], 0xa0000
	v_cvt_pk_bf16_f32 v180, v180, v206
	v_cvt_pk_bf16_f32 v207, v207, v227
	ds_bpermute_b32 v206, v226, v180
	ds_bpermute_b32 v207, v226, v207
	v_exp_f32_e32 v180, v136
	v_exp_f32_e32 v227, v132
	s_waitcnt lgkmcnt(0)
	global_store_dwordx2 v[208:209], v[206:207], off offset:32
	v_exp_f32_e32 v206, v135
	v_exp_f32_e32 v207, v134
	v_add_f32_e32 v180, 1.0, v180
	v_add_f32_e32 v227, 1.0, v227
	v_add_f32_e32 v206, 1.0, v206
	v_add_f32_e32 v207, 1.0, v207
	v_rcp_f32_e32 v180, v180
	v_rcp_f32_e32 v206, v206
	v_rcp_f32_e32 v207, v207
	v_rcp_f32_e32 v227, v227
	v_cvt_pk_bf16_f32 v180, v180, v206
	ds_bpermute_b32 v206, v226, v180
	v_cvt_pk_bf16_f32 v207, v207, v227
	ds_bpermute_b32 v207, v226, v207
	v_mul_f32_e32 v180, 0xbfb8aa3b, v32
	v_mul_f32_e32 v227, 0xbfb8aa3b, v35
	v_exp_f32_e32 v180, v180
	v_exp_f32_e32 v227, v227
	s_waitcnt lgkmcnt(0)
	global_store_dwordx2 v[208:209], v[206:207], off offset:256
	v_mul_f32_e32 v206, 0xbfb8aa3b, v33
	v_mul_f32_e32 v207, 0xbfb8aa3b, v34
	v_exp_f32_e32 v206, v206
	v_exp_f32_e32 v207, v207
	v_add_f32_e32 v180, 1.0, v180
	v_add_f32_e32 v227, 1.0, v227
	v_add_f32_e32 v206, 1.0, v206
	v_add_f32_e32 v207, 1.0, v207
	v_rcp_f32_e32 v180, v180
	v_rcp_f32_e32 v206, v206
	v_rcp_f32_e32 v207, v207
	v_rcp_f32_e32 v227, v227
	v_cvt_pk_bf16_f32 v180, v180, v206
	ds_bpermute_b32 v206, v226, v180
	v_cvt_pk_bf16_f32 v207, v207, v227
	ds_bpermute_b32 v207, v226, v207
	v_mul_f32_e32 v180, 0xbfb8aa3b, v28
	v_exp_f32_e32 v180, v180
	v_mul_f32_e32 v227, 0xbfb8aa3b, v23
	v_exp_f32_e32 v227, v227
	s_waitcnt lgkmcnt(0)
	global_store_dwordx2 v[208:209], v[206:207], off offset:288
	v_mul_f32_e32 v206, 0xbfb8aa3b, v29
	v_mul_f32_e32 v207, 0xbfb8aa3b, v30
	v_mul_f32_e32 v208, 0xbfb8aa3b, v31
	v_exp_f32_e32 v206, v206
	v_exp_f32_e32 v207, v207
	v_exp_f32_e32 v208, v208
	v_add_f32_e32 v180, 1.0, v180
	v_add_f32_e32 v206, 1.0, v206
	v_add_f32_e32 v207, 1.0, v207
	v_add_f32_e32 v208, 1.0, v208
	v_rcp_f32_e32 v180, v180
	v_rcp_f32_e32 v206, v206
	v_rcp_f32_e32 v207, v207
	v_rcp_f32_e32 v208, v208
	v_add_f32_e32 v227, 1.0, v227
	v_cvt_pk_bf16_f32 v180, v180, v206
	ds_bpermute_b32 v206, v226, v180
	v_cvt_pk_bf16_f32 v207, v207, v208
	ds_bpermute_b32 v207, v226, v207
	v_lshl_add_u64 v[208:209], v[130:131], 0, s[4:5]
	s_mov_b32 s4, 0xa0000
	v_add_co_u32_e32 v228, vcc, s4, v130
	v_mul_f32_e32 v180, 0xbfb8aa3b, v20
	s_nop 0
	v_addc_co_u32_e32 v229, vcc, 0, v131, vcc
	s_waitcnt lgkmcnt(0)
	global_store_dwordx2 v[228:229], v[206:207], off
	v_mul_f32_e32 v206, 0xbfb8aa3b, v21
	v_mul_f32_e32 v207, 0xbfb8aa3b, v22
	v_exp_f32_e32 v180, v180
	v_exp_f32_e32 v206, v206
	v_exp_f32_e32 v207, v207
	v_rcp_f32_e32 v227, v227
	v_add_f32_e32 v180, 1.0, v180
	v_add_f32_e32 v206, 1.0, v206
	v_add_f32_e32 v207, 1.0, v207
	v_rcp_f32_e32 v180, v180
	v_rcp_f32_e32 v206, v206
	v_rcp_f32_e32 v207, v207
	s_mov_b64 s[4:5], 0xb0000
	v_cvt_pk_bf16_f32 v180, v180, v206
	v_cvt_pk_bf16_f32 v207, v207, v227
	ds_bpermute_b32 v206, v226, v180
	ds_bpermute_b32 v207, v226, v207
	v_mul_f32_e32 v180, 0xbfb8aa3b, v24
	v_mul_f32_e32 v227, 0xbfb8aa3b, v27
	v_exp_f32_e32 v180, v180
	v_exp_f32_e32 v227, v227
	s_waitcnt lgkmcnt(0)
	global_store_dwordx2 v[208:209], v[206:207], off offset:32
	v_mul_f32_e32 v206, 0xbfb8aa3b, v25
	v_mul_f32_e32 v207, 0xbfb8aa3b, v26
	v_exp_f32_e32 v206, v206
	v_exp_f32_e32 v207, v207
	v_add_f32_e32 v180, 1.0, v180
	v_add_f32_e32 v227, 1.0, v227
	v_add_f32_e32 v206, 1.0, v206
	v_add_f32_e32 v207, 1.0, v207
	v_rcp_f32_e32 v180, v180
	v_rcp_f32_e32 v206, v206
	v_rcp_f32_e32 v207, v207
	v_rcp_f32_e32 v227, v227
	v_cvt_pk_bf16_f32 v180, v180, v206
	ds_bpermute_b32 v206, v226, v180
	v_cvt_pk_bf16_f32 v207, v207, v227
	ds_bpermute_b32 v207, v226, v207
	v_mul_f32_e32 v180, 0xbfb8aa3b, v16
	v_mul_f32_e32 v227, 0xbfb8aa3b, v19
	v_exp_f32_e32 v180, v180
	v_exp_f32_e32 v227, v227
	s_waitcnt lgkmcnt(0)
	global_store_dwordx2 v[208:209], v[206:207], off offset:256
	v_mul_f32_e32 v206, 0xbfb8aa3b, v17
	v_mul_f32_e32 v207, 0xbfb8aa3b, v18
	v_exp_f32_e32 v206, v206
	v_exp_f32_e32 v207, v207
	v_add_f32_e32 v180, 1.0, v180
	v_add_f32_e32 v227, 1.0, v227
	v_add_f32_e32 v206, 1.0, v206
	v_add_f32_e32 v207, 1.0, v207
	v_rcp_f32_e32 v180, v180
	v_rcp_f32_e32 v206, v206
	v_rcp_f32_e32 v207, v207
	v_rcp_f32_e32 v227, v227
	v_cvt_pk_bf16_f32 v180, v180, v206
	ds_bpermute_b32 v206, v226, v180
	v_cvt_pk_bf16_f32 v207, v207, v227
	ds_bpermute_b32 v207, v226, v207
	v_mul_f32_e32 v180, 0xbfb8aa3b, v12
	v_exp_f32_e32 v180, v180
	s_waitcnt lgkmcnt(0)
	global_store_dwordx2 v[208:209], v[206:207], off offset:288
	v_mul_f32_e32 v206, 0xbfb8aa3b, v13
	v_mul_f32_e32 v207, 0xbfb8aa3b, v14
	v_mul_f32_e32 v208, 0xbfb8aa3b, v15
	v_exp_f32_e32 v206, v206
	v_exp_f32_e32 v207, v207
	v_exp_f32_e32 v208, v208
	v_add_f32_e32 v180, 1.0, v180
	v_add_f32_e32 v206, 1.0, v206
	v_add_f32_e32 v207, 1.0, v207
	v_add_f32_e32 v208, 1.0, v208
	v_rcp_f32_e32 v180, v180
	v_rcp_f32_e32 v206, v206
	v_rcp_f32_e32 v207, v207
	v_rcp_f32_e32 v208, v208
	v_cvt_pk_bf16_f32 v180, v180, v206
	ds_bpermute_b32 v206, v226, v180
	v_cvt_pk_bf16_f32 v207, v207, v208
	ds_bpermute_b32 v207, v226, v207
	v_lshl_add_u64 v[208:209], v[130:131], 0, s[4:5]
	s_mov_b32 s4, 0xb0000
	v_add_co_u32_e32 v130, vcc, s4, v130
	v_mul_f32_e32 v180, 0xbfb8aa3b, v6
	s_nop 0
	v_addc_co_u32_e32 v131, vcc, 0, v131, vcc
	s_waitcnt lgkmcnt(0)
	global_store_dwordx2 v[130:131], v[206:207], off
	v_mul_f32_e32 v130, 0xbfb8aa3b, v4
	v_mul_f32_e32 v131, 0xbfb8aa3b, v5
	v_mul_f32_e32 v206, 0xbfb8aa3b, v7
	v_exp_f32_e32 v130, v130
	v_exp_f32_e32 v131, v131
	v_exp_f32_e32 v180, v180
	v_exp_f32_e32 v206, v206
	v_add_f32_e32 v130, 1.0, v130
	v_add_f32_e32 v131, 1.0, v131
	v_add_f32_e32 v180, 1.0, v180
	v_add_f32_e32 v206, 1.0, v206
	v_rcp_f32_e32 v130, v130
	v_rcp_f32_e32 v131, v131
	v_rcp_f32_e32 v180, v180
	v_rcp_f32_e32 v206, v206
	s_mov_b64 s[4:5], 0
	v_cvt_pk_bf16_f32 v130, v130, v131
	ds_bpermute_b32 v130, v226, v130
	v_cvt_pk_bf16_f32 v131, v180, v206
	ds_bpermute_b32 v131, v226, v131
	v_mul_f32_e32 v180, 0xbfb8aa3b, v10
	v_mul_f32_e32 v206, 0xbfb8aa3b, v11
	v_exp_f32_e32 v180, v180
	v_exp_f32_e32 v206, v206
	s_waitcnt lgkmcnt(0)
	global_store_dwordx2 v[208:209], v[130:131], off offset:32
	v_mul_f32_e32 v130, 0xbfb8aa3b, v8
	v_mul_f32_e32 v131, 0xbfb8aa3b, v9
	v_exp_f32_e32 v130, v130
	v_exp_f32_e32 v131, v131
	v_add_f32_e32 v180, 1.0, v180
	v_add_f32_e32 v206, 1.0, v206
	v_add_f32_e32 v130, 1.0, v130
	v_add_f32_e32 v131, 1.0, v131
	v_rcp_f32_e32 v130, v130
	v_rcp_f32_e32 v131, v131
	v_rcp_f32_e32 v180, v180
	v_rcp_f32_e32 v206, v206
	v_cvt_pk_bf16_f32 v130, v130, v131
	ds_bpermute_b32 v130, v226, v130
	v_cvt_pk_bf16_f32 v131, v180, v206
	ds_bpermute_b32 v131, v226, v131
	v_mul_f32_e32 v180, 0xbfb8aa3b, v2
	v_mul_f32_e32 v206, 0xbfb8aa3b, v3
	v_exp_f32_e32 v180, v180
	v_exp_f32_e32 v206, v206
	s_waitcnt lgkmcnt(0)
	global_store_dwordx2 v[208:209], v[130:131], off offset:256
	v_mul_f32_e32 v130, 0xbfb8aa3b, v0
	v_mul_f32_e32 v131, 0xbfb8aa3b, v1
	v_exp_f32_e32 v130, v130
	v_exp_f32_e32 v131, v131
	v_add_f32_e32 v180, 1.0, v180
	v_add_f32_e32 v206, 1.0, v206
	v_add_f32_e32 v130, 1.0, v130
	v_add_f32_e32 v131, 1.0, v131
	v_rcp_f32_e32 v130, v130
	v_rcp_f32_e32 v131, v131
	v_rcp_f32_e32 v180, v180
	v_rcp_f32_e32 v206, v206
	v_cvt_pk_bf16_f32 v130, v130, v131
	ds_bpermute_b32 v130, v226, v130
	v_cvt_pk_bf16_f32 v131, v180, v206
	ds_bpermute_b32 v131, v226, v131
	s_waitcnt lgkmcnt(0)
	global_store_dwordx2 v[208:209], v[130:131], off offset:288

.LBB0_1024:
	s_waitcnt lgkmcnt(0)
	ds_read_b128 v[128:131], v179
	ds_read_b128 v[132:135], v179 offset:1024
	ds_read_b128 v[136:139], v179 offset:2048
	ds_read_b128 v[140:143], v179 offset:3072
	s_add_i32 s62, s36, 2
	s_add_u32 s37, s4, 0xfff80080
	s_addc_u32 s38, s5, -1
	s_cmp_eq_u32 s59, s36
	s_cselect_b32 s36, s58, s60
	s_cselect_b32 s39, s21, s38
	s_cselect_b32 s38, s25, s37
	s_cselect_b32 s37, s23, s61

	s_add_i32 m0, s31, 0xc000
	ds_read_b128 v[144:147], v190
	ds_read_b128 v[148:151], v190 offset:1024
	ds_read_b128 v[152:155], v190 offset:2048
	ds_read_b128 v[156:159], v190 offset:3072
	ds_read_b128 v[180:183], v190 offset:4096
	ds_read_b128 v[184:187], v190 offset:5120
	ds_read_b128 v[194:197], v190 offset:6144
	ds_read_b128 v[198:201], v190 offset:7168
	global_load_lds_dwordx4 v162, s[4:5]
	s_add_i32 m0, s31, 0xe000
	s_nop 0

	global_load_lds_dwordx4 v164, s[4:5]
	s_waitcnt lgkmcnt(8)
	s_barrier
	s_waitcnt lgkmcnt(0)


	v_mfma_f32_16x16x32_bf16 v[124:127], v[128:131], v[144:147], v[124:127]
	v_mfma_f32_16x16x32_bf16 v[120:123], v[136:139], v[144:147], v[120:123]
	v_mfma_f32_16x16x32_bf16 v[116:119], v[128:131], v[152:155], v[116:119]
	v_mfma_f32_16x16x32_bf16 v[104:107], v[136:139], v[152:155], v[104:107]
	v_mfma_f32_16x16x32_bf16 v[96:99], v[128:131], v[180:183], v[96:99]
	v_mfma_f32_16x16x32_bf16 v[88:91], v[136:139], v[180:183], v[88:91]
	v_mfma_f32_16x16x32_bf16 v[80:83], v[128:131], v[194:197], v[80:83]
	v_mfma_f32_16x16x32_bf16 v[72:75], v[136:139], v[194:197], v[72:75]
	v_mfma_f32_16x16x32_bf16 v[124:127], v[132:135], v[148:151], v[124:127]
	v_mfma_f32_16x16x32_bf16 v[120:123], v[140:143], v[148:151], v[120:123]
	v_mfma_f32_16x16x32_bf16 v[116:119], v[132:135], v[156:159], v[116:119]
	v_mfma_f32_16x16x32_bf16 v[104:107], v[140:143], v[156:159], v[104:107]
	v_mfma_f32_16x16x32_bf16 v[96:99], v[132:135], v[184:187], v[96:99]
	v_mfma_f32_16x16x32_bf16 v[88:91], v[140:143], v[184:187], v[88:91]
	v_mfma_f32_16x16x32_bf16 v[80:83], v[132:135], v[198:201], v[80:83]
	v_mfma_f32_16x16x32_bf16 v[72:75], v[140:143], v[198:201], v[72:75]

	s_barrier
	s_add_i32 s63, s52, s42
	s_add_u32 s66, s36, s14
	s_addc_u32 s67, s37, s15
	s_mov_b32 m0, s63
	ds_read_b128 v[202:205], v191
	ds_read_b128 v[206:209], v191 offset:1024
	ds_read_b128 v[222:225], v191 offset:2048
	ds_read_b128 v[226:229], v191 offset:3072
	global_load_lds_dwordx4 v172, s[36:37]
	s_add_i32 m0, s63, 0x2000
	s_nop 0

	global_load_lds_dwordx4 v174, s[36:37]
	s_barrier
	s_waitcnt lgkmcnt(0)


	v_mfma_f32_16x16x32_bf16 v[112:115], v[202:205], v[144:147], v[112:115]
	v_mfma_f32_16x16x32_bf16 v[108:111], v[222:225], v[144:147], v[108:111]
	v_mfma_f32_16x16x32_bf16 v[100:103], v[202:205], v[152:155], v[100:103]
	v_mfma_f32_16x16x32_bf16 v[92:95], v[222:225], v[152:155], v[92:95]
	v_mfma_f32_16x16x32_bf16 v[84:87], v[202:205], v[180:183], v[84:87]
	v_mfma_f32_16x16x32_bf16 v[76:79], v[222:225], v[180:183], v[76:79]
	v_mfma_f32_16x16x32_bf16 v[68:71], v[202:205], v[194:197], v[68:71]
	v_mfma_f32_16x16x32_bf16 v[64:67], v[222:225], v[194:197], v[64:67]
	v_mfma_f32_16x16x32_bf16 v[112:115], v[206:209], v[148:151], v[112:115]
	v_mfma_f32_16x16x32_bf16 v[108:111], v[226:229], v[148:151], v[108:111]
	v_mfma_f32_16x16x32_bf16 v[100:103], v[206:209], v[156:159], v[100:103]
	v_mfma_f32_16x16x32_bf16 v[92:95], v[226:229], v[156:159], v[92:95]
	v_mfma_f32_16x16x32_bf16 v[84:87], v[206:209], v[184:187], v[84:87]
	v_mfma_f32_16x16x32_bf16 v[76:79], v[226:229], v[184:187], v[76:79]
	v_mfma_f32_16x16x32_bf16 v[68:71], v[206:209], v[198:201], v[68:71]
	v_mfma_f32_16x16x32_bf16 v[64:67], v[226:229], v[198:201], v[64:67]

	s_mov_b32 m0, s31
	s_add_u32 s68, s38, s14
	s_addc_u32 s69, s39, s15
	s_barrier
	ds_read_b128 v[144:147], v190 offset:16384
	ds_read_b128 v[148:151], v190 offset:17408
	ds_read_b128 v[152:155], v190 offset:18432
	ds_read_b128 v[156:159], v190 offset:19456
	ds_read_b128 v[180:183], v190 offset:20480
	ds_read_b128 v[184:187], v190 offset:21504
	ds_read_b128 v[194:197], v190 offset:22528
	ds_read_b128 v[198:201], v190 offset:23552
	global_load_lds_dwordx4 v172, s[38:39]
	s_mov_b32 m0, s35
	s_nop 0

	global_load_lds_dwordx4 v174, s[38:39]
	s_barrier
	s_waitcnt lgkmcnt(0)


	v_mfma_f32_16x16x32_bf16 v[60:63], v[128:131], v[144:147], v[60:63]
	v_mfma_f32_16x16x32_bf16 v[56:59], v[136:139], v[144:147], v[56:59]
	v_mfma_f32_16x16x32_bf16 v[52:55], v[128:131], v[152:155], v[52:55]
	v_mfma_f32_16x16x32_bf16 v[40:43], v[136:139], v[152:155], v[40:43]
	v_mfma_f32_16x16x32_bf16 v[36:39], v[128:131], v[180:183], v[36:39]
	v_mfma_f32_16x16x32_bf16 v[24:27], v[136:139], v[180:183], v[24:27]
	v_mfma_f32_16x16x32_bf16 v[20:23], v[128:131], v[194:197], v[20:23]
	v_mfma_f32_16x16x32_bf16 v[8:11], v[136:139], v[194:197], v[8:11]
	v_mfma_f32_16x16x32_bf16 v[60:63], v[132:135], v[148:151], v[60:63]
	v_mfma_f32_16x16x32_bf16 v[56:59], v[140:143], v[148:151], v[56:59]
	v_mfma_f32_16x16x32_bf16 v[52:55], v[132:135], v[156:159], v[52:55]
	v_mfma_f32_16x16x32_bf16 v[40:43], v[140:143], v[156:159], v[40:43]
	v_mfma_f32_16x16x32_bf16 v[36:39], v[132:135], v[184:187], v[36:39]
	v_mfma_f32_16x16x32_bf16 v[24:27], v[140:143], v[184:187], v[24:27]
	v_mfma_f32_16x16x32_bf16 v[20:23], v[132:135], v[198:201], v[20:23]
	v_mfma_f32_16x16x32_bf16 v[8:11], v[140:143], v[198:201], v[8:11]

	s_barrier
	s_add_u32 s64, s36, 0x80000
	s_addc_u32 s65, s37, 0
	s_add_i32 s63, s53, s42
	s_mov_b32 m0, s63
	s_nop 0

	global_load_lds_dwordx4 v172, s[64:65]
	s_add_i32 m0, s63, 0x2000
	s_nop 0

	global_load_lds_dwordx4 v174, s[64:65]
	s_waitcnt vmcnt(6)
	s_barrier

	v_mfma_f32_16x16x32_bf16 v[48:51], v[202:205], v[144:147], v[48:51]
	v_mfma_f32_16x16x32_bf16 v[44:47], v[222:225], v[144:147], v[44:47]
	v_mfma_f32_16x16x32_bf16 v[32:35], v[202:205], v[152:155], v[32:35]
	v_mfma_f32_16x16x32_bf16 v[28:31], v[222:225], v[152:155], v[28:31]
	v_mfma_f32_16x16x32_bf16 v[16:19], v[202:205], v[180:183], v[16:19]
	v_mfma_f32_16x16x32_bf16 v[12:15], v[222:225], v[180:183], v[12:15]
	v_mfma_f32_16x16x32_bf16 v[4:7], v[202:205], v[194:197], v[4:7]
	v_mfma_f32_16x16x32_bf16 v[0:3], v[222:225], v[194:197], v[0:3]
	v_mfma_f32_16x16x32_bf16 v[48:51], v[206:209], v[148:151], v[48:51]
	v_mfma_f32_16x16x32_bf16 v[44:47], v[226:229], v[148:151], v[44:47]
	v_mfma_f32_16x16x32_bf16 v[32:35], v[206:209], v[156:159], v[32:35]
	v_mfma_f32_16x16x32_bf16 v[28:31], v[226:229], v[156:159], v[28:31]
	v_mfma_f32_16x16x32_bf16 v[16:19], v[206:209], v[184:187], v[16:19]
	v_mfma_f32_16x16x32_bf16 v[12:15], v[226:229], v[184:187], v[12:15]
	v_mfma_f32_16x16x32_bf16 v[4:7], v[206:209], v[198:201], v[4:7]
	v_mfma_f32_16x16x32_bf16 v[0:3], v[226:229], v[198:201], v[0:3]

	s_add_i32 s63, 0, 0x18000
	v_add_u32_e32 v140, s63, v177
	s_barrier
	ds_read_b128 v[128:131], v140
	ds_read_b128 v[132:135], v140 offset:1024
	ds_read_b128 v[136:139], v140 offset:2048
	ds_read_b128 v[140:143], v140 offset:3072
	s_add_u32 s38, s38, 0x80000
	s_addc_u32 s39, s39, 0
	s_mov_b32 m0, s43

	ds_read_b128 v[144:147], v190 offset:32768
	ds_read_b128 v[148:151], v190 offset:33792
	ds_read_b128 v[152:155], v190 offset:34816
	ds_read_b128 v[156:159], v190 offset:35840
	ds_read_b128 v[180:183], v190 offset:36864
	ds_read_b128 v[184:187], v190 offset:37888
	ds_read_b128 v[194:197], v190 offset:38912
	ds_read_b128 v[198:201], v190 offset:39936
	global_load_lds_dwordx4 v172, s[38:39]
	s_mov_b32 m0, s44
	s_nop 0

	global_load_lds_dwordx4 v174, s[38:39]
	s_waitcnt lgkmcnt(8)
	s_barrier
	s_waitcnt lgkmcnt(0)


	v_mfma_f32_16x16x32_bf16 v[124:127], v[128:131], v[144:147], v[124:127]
	v_mfma_f32_16x16x32_bf16 v[120:123], v[136:139], v[144:147], v[120:123]
	v_mfma_f32_16x16x32_bf16 v[116:119], v[128:131], v[152:155], v[116:119]
	v_mfma_f32_16x16x32_bf16 v[104:107], v[136:139], v[152:155], v[104:107]
	v_mfma_f32_16x16x32_bf16 v[96:99], v[128:131], v[180:183], v[96:99]
	v_mfma_f32_16x16x32_bf16 v[88:91], v[136:139], v[180:183], v[88:91]
	v_mfma_f32_16x16x32_bf16 v[80:83], v[128:131], v[194:197], v[80:83]
	v_mfma_f32_16x16x32_bf16 v[72:75], v[136:139], v[194:197], v[72:75]
	v_mfma_f32_16x16x32_bf16 v[124:127], v[132:135], v[148:151], v[124:127]
	v_mfma_f32_16x16x32_bf16 v[120:123], v[140:143], v[148:151], v[120:123]
	v_mfma_f32_16x16x32_bf16 v[116:119], v[132:135], v[156:159], v[116:119]
	v_mfma_f32_16x16x32_bf16 v[104:107], v[140:143], v[156:159], v[104:107]
	v_mfma_f32_16x16x32_bf16 v[96:99], v[132:135], v[184:187], v[96:99]
	v_mfma_f32_16x16x32_bf16 v[88:91], v[140:143], v[184:187], v[88:91]
	v_mfma_f32_16x16x32_bf16 v[80:83], v[132:135], v[198:201], v[80:83]
	v_mfma_f32_16x16x32_bf16 v[72:75], v[140:143], v[198:201], v[72:75]

	s_barrier
	s_add_i32 s38, 0, 0x1c000
	s_add_i32 s39, s63, s42
	v_add_u32_e32 v160, s38, v177

	s_mov_b32 m0, s39
	ds_read_b128 v[202:205], v160
	ds_read_b128 v[206:209], v160 offset:1024
	ds_read_b128 v[222:225], v160 offset:2048
	ds_read_b128 v[226:229], v160 offset:3072
	global_load_lds_dwordx4 v172, s[66:67]
	s_add_i32 m0, s39, 0x2000
	s_nop 0

	global_load_lds_dwordx4 v174, s[66:67]
	s_barrier
	s_waitcnt lgkmcnt(0)


	v_mfma_f32_16x16x32_bf16 v[112:115], v[202:205], v[144:147], v[112:115]
	v_mfma_f32_16x16x32_bf16 v[108:111], v[222:225], v[144:147], v[108:111]
	v_mfma_f32_16x16x32_bf16 v[100:103], v[202:205], v[152:155], v[100:103]
	v_mfma_f32_16x16x32_bf16 v[92:95], v[222:225], v[152:155], v[92:95]
	v_mfma_f32_16x16x32_bf16 v[84:87], v[202:205], v[180:183], v[84:87]
	v_mfma_f32_16x16x32_bf16 v[76:79], v[222:225], v[180:183], v[76:79]
	v_mfma_f32_16x16x32_bf16 v[68:71], v[202:205], v[194:197], v[68:71]
	v_mfma_f32_16x16x32_bf16 v[64:67], v[222:225], v[194:197], v[64:67]
	v_mfma_f32_16x16x32_bf16 v[112:115], v[206:209], v[148:151], v[112:115]
	v_mfma_f32_16x16x32_bf16 v[108:111], v[226:229], v[148:151], v[108:111]
	v_mfma_f32_16x16x32_bf16 v[100:103], v[206:209], v[156:159], v[100:103]
	v_mfma_f32_16x16x32_bf16 v[92:95], v[226:229], v[156:159], v[92:95]
	v_mfma_f32_16x16x32_bf16 v[84:87], v[206:209], v[184:187], v[84:87]
	v_mfma_f32_16x16x32_bf16 v[76:79], v[226:229], v[184:187], v[76:79]
	v_mfma_f32_16x16x32_bf16 v[68:71], v[206:209], v[198:201], v[68:71]
	v_mfma_f32_16x16x32_bf16 v[64:67], v[226:229], v[198:201], v[64:67]

	s_mov_b32 m0, s48

	s_barrier
	ds_read_b128 v[144:147], v190 offset:49152
	ds_read_b128 v[148:151], v190 offset:50176
	ds_read_b128 v[152:155], v190 offset:51200
	ds_read_b128 v[156:159], v190 offset:52224
	ds_read_b128 v[180:183], v190 offset:53248
	ds_read_b128 v[184:187], v190 offset:54272
	ds_read_b128 v[194:197], v190 offset:55296
	ds_read_b128 v[198:201], v190 offset:56320
	global_load_lds_dwordx4 v172, s[68:69]
	s_mov_b32 m0, s49
	s_nop 0

	global_load_lds_dwordx4 v174, s[68:69]
	s_barrier
	s_waitcnt lgkmcnt(0)


	v_mfma_f32_16x16x32_bf16 v[60:63], v[128:131], v[144:147], v[60:63]
	v_mfma_f32_16x16x32_bf16 v[56:59], v[136:139], v[144:147], v[56:59]
	v_mfma_f32_16x16x32_bf16 v[52:55], v[128:131], v[152:155], v[52:55]
	v_mfma_f32_16x16x32_bf16 v[40:43], v[136:139], v[152:155], v[40:43]
	v_mfma_f32_16x16x32_bf16 v[36:39], v[128:131], v[180:183], v[36:39]
	v_mfma_f32_16x16x32_bf16 v[24:27], v[136:139], v[180:183], v[24:27]
	v_mfma_f32_16x16x32_bf16 v[20:23], v[128:131], v[194:197], v[20:23]
	v_mfma_f32_16x16x32_bf16 v[8:11], v[136:139], v[194:197], v[8:11]
	v_mfma_f32_16x16x32_bf16 v[60:63], v[132:135], v[148:151], v[60:63]
	v_mfma_f32_16x16x32_bf16 v[56:59], v[140:143], v[148:151], v[56:59]
	v_mfma_f32_16x16x32_bf16 v[52:55], v[132:135], v[156:159], v[52:55]
	v_mfma_f32_16x16x32_bf16 v[40:43], v[140:143], v[156:159], v[40:43]
	v_mfma_f32_16x16x32_bf16 v[36:39], v[132:135], v[184:187], v[36:39]
	v_mfma_f32_16x16x32_bf16 v[24:27], v[140:143], v[184:187], v[24:27]
	v_mfma_f32_16x16x32_bf16 v[20:23], v[132:135], v[198:201], v[20:23]
	v_mfma_f32_16x16x32_bf16 v[8:11], v[140:143], v[198:201], v[8:11]

	s_barrier
	s_add_u32 s36, s36, 0x80080
	s_addc_u32 s37, s37, 0
	s_add_i32 s38, s38, s42
	s_mov_b32 m0, s38
	s_nop 0

	global_load_lds_dwordx4 v172, s[36:37]
	s_add_i32 m0, s38, 0x2000
	s_nop 0

	global_load_lds_dwordx4 v174, s[36:37]
	s_waitcnt vmcnt(6)
	s_barrier

	v_mfma_f32_16x16x32_bf16 v[48:51], v[202:205], v[144:147], v[48:51]
	v_mfma_f32_16x16x32_bf16 v[44:47], v[222:225], v[144:147], v[44:47]
	v_mfma_f32_16x16x32_bf16 v[32:35], v[202:205], v[152:155], v[32:35]
	v_mfma_f32_16x16x32_bf16 v[28:31], v[222:225], v[152:155], v[28:31]
	v_mfma_f32_16x16x32_bf16 v[16:19], v[202:205], v[180:183], v[16:19]
	v_mfma_f32_16x16x32_bf16 v[12:15], v[222:225], v[180:183], v[12:15]
	v_mfma_f32_16x16x32_bf16 v[4:7], v[202:205], v[194:197], v[4:7]
	v_mfma_f32_16x16x32_bf16 v[0:3], v[222:225], v[194:197], v[0:3]
	v_mfma_f32_16x16x32_bf16 v[48:51], v[206:209], v[148:151], v[48:51]
	v_mfma_f32_16x16x32_bf16 v[44:47], v[226:229], v[148:151], v[44:47]
	v_mfma_f32_16x16x32_bf16 v[32:35], v[206:209], v[156:159], v[32:35]
	v_mfma_f32_16x16x32_bf16 v[28:31], v[226:229], v[156:159], v[28:31]
	v_mfma_f32_16x16x32_bf16 v[16:19], v[206:209], v[184:187], v[16:19]
	v_mfma_f32_16x16x32_bf16 v[12:15], v[226:229], v[184:187], v[12:15]
	v_mfma_f32_16x16x32_bf16 v[4:7], v[206:209], v[198:201], v[4:7]
	v_mfma_f32_16x16x32_bf16 v[0:3], v[226:229], v[198:201], v[0:3]

	s_add_u32 s4, s4, 0x100
	s_addc_u32 s5, s5, 0
	s_add_u32 s60, s60, 0x100
	s_addc_u32 s61, s61, 0
	s_cmp_ge_i32 s62, s17
	s_mov_b32 s36, s62
	s_barrier
	s_cbranch_scc0 .LBB0_1024
	v_mov_b32_e32 v128, v210
	v_mov_b32_e32 v129, v169
	s_cmp_lt_i32 s12, 0
	v_lshl_add_u32 v128, v128, 4, v129
	v_ashrrev_i32_e32 v166, 2, v128
	v_and_b32_e32 v160, 3, v129
	v_and_b32_e32 v128, -4, v128
	v_lshl_add_u32 v193, v160, 6, v128
	s_mov_b64 s[4:5], -1
	s_cbranch_scc0 .LBB0_1043
	s_lshl_b32 s4, s30, 8
	v_lshl_or_b32 v128, v160, 2, s4
	s_lshl_b32 s4, s34, 8
	v_or_b32_e32 v180, s47, v128
	s_add_i32 s4, s4, s46
	v_readlane_b32 s60, v254, 6
	v_ashrrev_i32_e32 v181, 31, v180
	v_add_u32_e32 v184, s4, v166
	s_cmp_lt_i32 s34, 32
	v_readlane_b32 s61, v254, 7
	v_lshlrev_b64 v[128:129], 2, v[180:181]
	v_readlane_b32 s62, v254, 8
	v_readlane_b32 s63, v254, 9
	v_readlane_b32 s64, v254, 10
	v_readlane_b32 s65, v254, 11
	v_readlane_b32 s66, v254, 12
	v_readlane_b32 s67, v254, 13
	v_readlane_b32 s68, v254, 14
	v_readlane_b32 s69, v254, 15
	v_readlane_b32 s70, v254, 16
	v_readlane_b32 s71, v254, 17
	v_readlane_b32 s72, v254, 18
	v_readlane_b32 s73, v254, 19
	v_readlane_b32 s74, v254, 20
	v_readlane_b32 s75, v254, 21
	s_cselect_b32 s5, s61, s51
	s_cselect_b32 s4, s60, s50
	v_ashrrev_i32_e32 v185, 31, v184
	v_lshl_add_u64 v[182:183], s[4:5], 0, v[128:129]
	v_lshlrev_b64 v[130:131], 13, v[184:185]
	v_readlane_b32 s60, v254, 22
	v_lshl_add_u64 v[136:137], v[182:183], 0, v[130:131]
	v_readlane_b32 s61, v254, 23
	v_readlane_b32 s68, v254, 30
	v_readlane_b32 s69, v254, 31
	global_load_dwordx4 v[196:199], v[136:137], off nt
	global_load_dwordx4 v[200:203], v[136:137], off offset:64 nt
	global_load_dwordx4 v[204:207], v[136:137], off offset:512 nt
	s_mov_b64 s[60:61], s[68:69]
	v_lshl_add_u64 v[138:139], s[60:61], 0, v[128:129]
	global_load_dwordx4 v[140:143], v[138:139], off
	global_load_dwordx4 v[132:135], v[138:139], off offset:64
	global_load_dwordx4 v[128:131], v[138:139], off offset:512
	global_load_dwordx4 v[222:225], v[136:137], off offset:576 nt
	v_and_b32_e32 v145, 64, v192
	global_load_dwordx4 v[136:139], v[138:139], off offset:576
	v_xor_b32_e32 v144, 1, v192
	v_add_u32_e32 v194, 64, v145
	v_add_u32_e32 v186, 16, v184
	v_cmp_lt_i32_e64 s[4:5], v144, v194
	v_ashrrev_i32_e32 v187, 31, v186
	ds_bpermute_b32 v188, v193, v124
	v_cndmask_b32_e64 v195, v192, v144, s[4:5]
	v_lshlrev_b64 v[144:145], 13, v[186:187]
	v_lshl_add_u64 v[144:145], v[182:183], 0, v[144:145]
	global_load_dwordx4 v[156:159], v[144:145], off nt
	global_load_dwordx4 v[152:155], v[144:145], off offset:64 nt
	global_load_dwordx4 v[148:151], v[144:145], off offset:512 nt
	s_nop 0
	global_load_dwordx4 v[144:147], v[144:145], off offset:576 nt
	ds_bpermute_b32 v189, v193, v125
	ds_bpermute_b32 v208, v193, v126
	ds_bpermute_b32 v209, v193, v127
	ds_bpermute_b32 v226, v193, v120
	ds_bpermute_b32 v227, v193, v121
	ds_bpermute_b32 v228, v193, v122
	ds_bpermute_b32 v229, v193, v123
	ds_bpermute_b32 v230, v193, v112
	ds_bpermute_b32 v231, v193, v113
	v_readlane_b32 s64, v254, 26
	v_readlane_b32 s65, v254, 27
	v_readlane_b32 s66, v254, 28
	v_readlane_b32 s67, v254, 29
	v_readlane_b32 s72, v254, 34
	v_readlane_b32 s73, v254, 35
	v_readlane_b32 s74, v254, 36
	v_readlane_b32 s75, v254, 37
	s_mov_b64 s[64:65], s[72:73]
	ds_bpermute_b32 v232, v193, v114
	ds_bpermute_b32 v233, v193, v115
	v_lshlrev_b64 v[234:235], 11, v[184:185]
	s_mov_b64 s[66:67], s[74:75]
	v_lshl_add_u64 v[234:235], v[234:235], 0, v[180:181]
	v_xor_b32_e32 v167, 2, v192
	v_lshl_add_u64 v[236:237], v[234:235], 2, s[66:67]
	v_readlane_b32 s2, v254, 54
	v_cmp_lt_i32_e64 s[4:5], v167, v194
	v_lshlrev_b32_e32 v194, 2, v195
	v_lshlrev_b64 v[234:235], 1, v[234:235]
	v_readlane_b32 s3, v254, 55
	v_or_b32_e32 v240, 32, v234
	v_mov_b32_e32 v241, v235
	v_lshl_add_u64 v[238:239], s[2:3], 0, v[234:235]
	v_lshl_add_u64 v[240:241], s[2:3], 0, v[240:241]
	v_cndmask_b32_e64 v167, v192, v167, s[4:5]
	v_lshlrev_b32_e32 v167, 2, v167
	v_cmp_eq_u32_e32 vcc, 0, v160
	v_readlane_b32 s62, v254, 24
	v_readlane_b32 s63, v254, 25
	v_readlane_b32 s70, v254, 32
	v_readlane_b32 s71, v254, 33
	s_waitcnt vmcnt(0) lgkmcnt(0)
	v_pk_add_f32 v[198:199], v[198:199], v[208:209]
	v_pk_add_f32 v[196:197], v[196:197], v[188:189]
	v_pk_add_f32 v[202:203], v[202:203], v[228:229]
	v_pk_add_f32 v[200:201], v[200:201], v[226:227]
	v_pk_add_f32 v[204:205], v[204:205], v[230:231]
	v_mul_f32_e32 v195, v197, v197
	v_mul_f32_e32 v221, v199, v199
	global_store_dwordx4 v[236:237], v[196:199], off
	v_pk_mul_f32 v[188:189], v[142:143], v[198:199]
	v_pk_mul_f32 v[208:209], v[140:141], v[196:197]
	v_mul_f32_e32 v199, v201, v201
	v_mul_f32_e32 v230, v203, v203
	v_pk_mul_f32 v[226:227], v[134:135], v[202:203]
	v_pk_mul_f32 v[228:229], v[132:133], v[200:201]
	v_fmac_f32_e32 v195, v196, v196
	v_fmac_f32_e32 v221, v198, v198
	v_cvt_pk_bf16_f32 v196, v208, v209
	v_cvt_pk_bf16_f32 v197, v188, v189
	v_fmac_f32_e32 v199, v200, v200
	v_fmac_f32_e32 v230, v202, v202
	v_pk_add_f32 v[206:207], v[206:207], v[232:233]
	v_cvt_pk_bf16_f32 v188, v228, v229
	v_cvt_pk_bf16_f32 v189, v226, v227
	v_add_f32_e32 v195, v195, v221
	global_store_dwordx2 v[238:239], v[196:197], off
	v_add_f32_e32 v196, v199, v230
	global_store_dwordx4 v[236:237], v[200:203], off offset:64
	global_store_dwordx2 v[240:241], v[188:189], off
	v_add_f32_e32 v188, v195, v196
	v_mul_f32_e32 v189, v205, v205
	v_mul_f32_e32 v195, v207, v207
	v_fmac_f32_e32 v189, v204, v204
	v_fmac_f32_e32 v195, v206, v206
	ds_bpermute_b32 v200, v193, v108
	ds_bpermute_b32 v198, v193, v110
	ds_bpermute_b32 v199, v193, v111
	ds_bpermute_b32 v201, v193, v109
	v_add_f32_e32 v189, v189, v195
	v_add_f32_e32 v195, v188, v189
	v_pk_mul_f32 v[188:189], v[130:131], v[206:207]
	v_pk_mul_f32 v[196:197], v[128:129], v[204:205]
	global_store_dwordx4 v[236:237], v[204:207], off offset:512
	v_cvt_pk_bf16_f32 v196, v196, v197
	v_cvt_pk_bf16_f32 v197, v188, v189
	v_or_b32_e32 v188, 0x100, v234
	v_mov_b32_e32 v189, v235
	v_lshl_add_u64 v[188:189], s[2:3], 0, v[188:189]
	global_store_dwordx2 v[188:189], v[196:197], off
	s_waitcnt lgkmcnt(1)
	v_pk_add_f32 v[198:199], v[224:225], v[198:199]
	s_waitcnt lgkmcnt(0)
	v_pk_add_f32 v[196:197], v[222:223], v[200:201]
	v_mul_f32_e32 v189, v199, v199
	v_mul_f32_e32 v188, v197, v197
	v_fmac_f32_e32 v188, v196, v196
	v_fmac_f32_e32 v189, v198, v198
	v_add_f32_e32 v188, v188, v189
	v_add_f32_e32 v195, v195, v188
	ds_bpermute_b32 v200, v194, v195
	v_pk_mul_f32 v[188:189], v[136:137], v[196:197]
	global_store_dwordx4 v[236:237], v[196:199], off offset:576
	v_or_b32_e32 v234, 0x120, v234
	s_nop 0
	v_cvt_pk_bf16_f32 v196, v188, v189
	s_waitcnt lgkmcnt(0)
	v_add_f32_e32 v188, v195, v200
	ds_bpermute_b32 v189, v167, v188
	v_pk_mul_f32 v[198:199], v[138:139], v[198:199]
	s_nop 0
	v_cvt_pk_bf16_f32 v197, v198, v199
	v_lshl_add_u64 v[198:199], s[2:3], 0, v[234:235]
	global_store_dwordx2 v[198:199], v[196:197], off
	s_and_saveexec_b64 s[4:5], vcc
	s_cbranch_execz .LBB0_1028
	s_waitcnt lgkmcnt(0)
	v_add_f32_e32 v195, v188, v189
	s_lshl_b32 s36, s30, 2
	v_lshlrev_b64 v[188:189], 7, v[184:185]
	s_ashr_i32 s37, s36, 31
	v_lshl_add_u64 v[188:189], s[10:11], 0, v[188:189]
	v_lshl_add_u64 v[188:189], s[36:37], 2, v[188:189]
	s_lshl_b32 s36, s45, 2
	s_mov_b32 s37, s13
	v_lshl_add_u64 v[188:189], v[188:189], 0, s[36:37]
	global_store_dword v[188:189], v195, off

.LBB0_1167:
	ds_read_b128 v[148:151], v143
	ds_read_b128 v[152:155], v143 offset:1024
	ds_read_b128 v[156:159], v143 offset:2048
	ds_read_b128 v[160:163], v143 offset:3072
	s_add_u32 s24, s22, 0xfff80080
	s_addc_u32 s25, s23, -1
	s_cmp_eq_u32 s53, 28
	s_cselect_b32 s27, s15, s25
	s_cselect_b32 s26, s49, s24
	s_cselect_b32 s25, s13, s52
	s_cselect_b32 s24, s50, s51

	s_add_i32 m0, s21, 0xc000
	ds_read_b128 v[164:167], v145
	ds_read_b128 v[176:179], v145 offset:1024
	ds_read_b128 v[180:183], v145 offset:2048
	ds_read_b128 v[184:187], v145 offset:3072
	ds_read_b128 v[188:191], v145 offset:4096
	ds_read_b128 v[192:195], v145 offset:5120
	ds_read_b128 v[196:199], v145 offset:6144
	ds_read_b128 v[200:203], v145 offset:7168
	global_load_lds_dwordx4 v128, s[22:23]
	s_add_i32 m0, s21, 0xe000
	s_nop 0

	global_load_lds_dwordx4 v130, s[22:23]
	s_waitcnt lgkmcnt(8)
	s_barrier
	s_waitcnt lgkmcnt(0)


	v_mfma_f32_16x16x32_bf16 v[124:127], v[148:151], v[164:167], v[124:127]
	v_mfma_f32_16x16x32_bf16 v[120:123], v[156:159], v[164:167], v[120:123]
	v_mfma_f32_16x16x32_bf16 v[116:119], v[148:151], v[180:183], v[116:119]
	v_mfma_f32_16x16x32_bf16 v[104:107], v[156:159], v[180:183], v[104:107]
	v_mfma_f32_16x16x32_bf16 v[96:99], v[148:151], v[188:191], v[96:99]
	v_mfma_f32_16x16x32_bf16 v[88:91], v[156:159], v[188:191], v[88:91]
	v_mfma_f32_16x16x32_bf16 v[80:83], v[148:151], v[196:199], v[80:83]
	v_mfma_f32_16x16x32_bf16 v[72:75], v[156:159], v[196:199], v[72:75]
	v_mfma_f32_16x16x32_bf16 v[124:127], v[152:155], v[176:179], v[124:127]
	v_mfma_f32_16x16x32_bf16 v[120:123], v[160:163], v[176:179], v[120:123]
	v_mfma_f32_16x16x32_bf16 v[116:119], v[152:155], v[184:187], v[116:119]
	v_mfma_f32_16x16x32_bf16 v[104:107], v[160:163], v[184:187], v[104:107]
	v_mfma_f32_16x16x32_bf16 v[96:99], v[152:155], v[192:195], v[96:99]
	v_mfma_f32_16x16x32_bf16 v[88:91], v[160:163], v[192:195], v[88:91]
	v_mfma_f32_16x16x32_bf16 v[80:83], v[152:155], v[200:203], v[80:83]
	v_mfma_f32_16x16x32_bf16 v[72:75], v[160:163], v[200:203], v[72:75]

	s_barrier
	s_add_i32 s54, s45, s31
	s_add_u32 s66, s24, s10
	s_addc_u32 s67, s25, s11
	s_mov_b32 m0, s54
	ds_read_b128 v[204:207], v147
	ds_read_b128 v[218:221], v147 offset:1024
	ds_read_b128 v[222:225], v147 offset:2048
	ds_read_b128 v[226:229], v147 offset:3072
	global_load_lds_dwordx4 v172, s[24:25]
	s_add_i32 m0, s54, 0x2000
	s_nop 0

	global_load_lds_dwordx4 v174, s[24:25]
	s_barrier
	s_waitcnt lgkmcnt(0)


	v_mfma_f32_16x16x32_bf16 v[112:115], v[204:207], v[164:167], v[112:115]
	v_mfma_f32_16x16x32_bf16 v[108:111], v[222:225], v[164:167], v[108:111]
	v_mfma_f32_16x16x32_bf16 v[100:103], v[204:207], v[180:183], v[100:103]
	v_mfma_f32_16x16x32_bf16 v[92:95], v[222:225], v[180:183], v[92:95]
	v_mfma_f32_16x16x32_bf16 v[84:87], v[204:207], v[188:191], v[84:87]
	v_mfma_f32_16x16x32_bf16 v[76:79], v[222:225], v[188:191], v[76:79]
	v_mfma_f32_16x16x32_bf16 v[68:71], v[204:207], v[196:199], v[68:71]
	v_mfma_f32_16x16x32_bf16 v[64:67], v[222:225], v[196:199], v[64:67]
	v_mfma_f32_16x16x32_bf16 v[112:115], v[218:221], v[176:179], v[112:115]
	v_mfma_f32_16x16x32_bf16 v[108:111], v[226:229], v[176:179], v[108:111]
	v_mfma_f32_16x16x32_bf16 v[100:103], v[218:221], v[184:187], v[100:103]
	v_mfma_f32_16x16x32_bf16 v[92:95], v[226:229], v[184:187], v[92:95]
	v_mfma_f32_16x16x32_bf16 v[84:87], v[218:221], v[192:195], v[84:87]
	v_mfma_f32_16x16x32_bf16 v[76:79], v[226:229], v[192:195], v[76:79]
	v_mfma_f32_16x16x32_bf16 v[68:71], v[218:221], v[200:203], v[68:71]
	v_mfma_f32_16x16x32_bf16 v[64:67], v[226:229], v[200:203], v[64:67]

	s_mov_b32 m0, s21
	s_add_u32 s68, s26, s10
	s_addc_u32 s69, s27, s11
	s_barrier
	ds_read_b128 v[164:167], v145 offset:16384
	ds_read_b128 v[176:179], v145 offset:17408
	ds_read_b128 v[180:183], v145 offset:18432
	ds_read_b128 v[184:187], v145 offset:19456
	ds_read_b128 v[188:191], v145 offset:20480
	ds_read_b128 v[192:195], v145 offset:21504
	ds_read_b128 v[196:199], v145 offset:22528
	ds_read_b128 v[200:203], v145 offset:23552
	global_load_lds_dwordx4 v172, s[26:27]
	s_mov_b32 m0, s35
	s_nop 0

	global_load_lds_dwordx4 v174, s[26:27]
	s_barrier
	s_waitcnt lgkmcnt(0)


	v_mfma_f32_16x16x32_bf16 v[60:63], v[148:151], v[164:167], v[60:63]
	v_mfma_f32_16x16x32_bf16 v[56:59], v[156:159], v[164:167], v[56:59]
	v_mfma_f32_16x16x32_bf16 v[48:51], v[148:151], v[180:183], v[48:51]
	v_mfma_f32_16x16x32_bf16 v[40:43], v[156:159], v[180:183], v[40:43]
	v_mfma_f32_16x16x32_bf16 v[32:35], v[148:151], v[188:191], v[32:35]
	v_mfma_f32_16x16x32_bf16 v[24:27], v[156:159], v[188:191], v[24:27]
	v_mfma_f32_16x16x32_bf16 v[16:19], v[148:151], v[196:199], v[16:19]
	v_mfma_f32_16x16x32_bf16 v[8:11], v[156:159], v[196:199], v[8:11]
	v_mfma_f32_16x16x32_bf16 v[60:63], v[152:155], v[176:179], v[60:63]
	v_mfma_f32_16x16x32_bf16 v[56:59], v[160:163], v[176:179], v[56:59]
	v_mfma_f32_16x16x32_bf16 v[48:51], v[152:155], v[184:187], v[48:51]
	v_mfma_f32_16x16x32_bf16 v[40:43], v[160:163], v[184:187], v[40:43]
	v_mfma_f32_16x16x32_bf16 v[32:35], v[152:155], v[192:195], v[32:35]
	v_mfma_f32_16x16x32_bf16 v[24:27], v[160:163], v[192:195], v[24:27]
	v_mfma_f32_16x16x32_bf16 v[16:19], v[152:155], v[200:203], v[16:19]
	v_mfma_f32_16x16x32_bf16 v[8:11], v[160:163], v[200:203], v[8:11]

	s_barrier
	s_add_u32 s54, s24, 0x80000
	s_addc_u32 s55, s25, 0
	s_add_i32 s56, s46, s31
	s_mov_b32 m0, s56
	s_nop 0

	global_load_lds_dwordx4 v172, s[54:55]
	s_add_i32 m0, s56, 0x2000
	s_nop 0

	global_load_lds_dwordx4 v174, s[54:55]
	s_waitcnt vmcnt(6)
	s_barrier

	v_mfma_f32_16x16x32_bf16 v[52:55], v[204:207], v[164:167], v[52:55]
	v_mfma_f32_16x16x32_bf16 v[44:47], v[222:225], v[164:167], v[44:47]
	v_mfma_f32_16x16x32_bf16 v[36:39], v[204:207], v[180:183], v[36:39]
	v_mfma_f32_16x16x32_bf16 v[28:31], v[222:225], v[180:183], v[28:31]
	v_mfma_f32_16x16x32_bf16 v[20:23], v[204:207], v[188:191], v[20:23]
	v_mfma_f32_16x16x32_bf16 v[12:15], v[222:225], v[188:191], v[12:15]
	v_mfma_f32_16x16x32_bf16 v[4:7], v[204:207], v[196:199], v[4:7]
	v_mfma_f32_16x16x32_bf16 v[0:3], v[222:225], v[196:199], v[0:3]
	v_mfma_f32_16x16x32_bf16 v[52:55], v[218:221], v[176:179], v[52:55]
	v_mfma_f32_16x16x32_bf16 v[44:47], v[226:229], v[176:179], v[44:47]
	v_mfma_f32_16x16x32_bf16 v[36:39], v[218:221], v[184:187], v[36:39]
	v_mfma_f32_16x16x32_bf16 v[28:31], v[226:229], v[184:187], v[28:31]
	v_mfma_f32_16x16x32_bf16 v[20:23], v[218:221], v[192:195], v[20:23]
	v_mfma_f32_16x16x32_bf16 v[12:15], v[226:229], v[192:195], v[12:15]
	v_mfma_f32_16x16x32_bf16 v[4:7], v[218:221], v[200:203], v[4:7]
	v_mfma_f32_16x16x32_bf16 v[0:3], v[226:229], v[200:203], v[0:3]

	s_add_i32 s54, 0, 0x18000
	v_add_u32_e32 v138, s54, v139
	s_barrier
	ds_read_b128 v[148:151], v138
	ds_read_b128 v[152:155], v138 offset:1024
	ds_read_b128 v[156:159], v138 offset:2048
	ds_read_b128 v[160:163], v138 offset:3072
	s_add_u32 s26, s26, 0x80000
	s_addc_u32 s27, s27, 0
	s_mov_b32 m0, s36

	ds_read_b128 v[164:167], v145 offset:32768
	ds_read_b128 v[176:179], v145 offset:33792
	ds_read_b128 v[180:183], v145 offset:34816
	ds_read_b128 v[184:187], v145 offset:35840
	ds_read_b128 v[188:191], v145 offset:36864
	ds_read_b128 v[192:195], v145 offset:37888
	ds_read_b128 v[196:199], v145 offset:38912
	ds_read_b128 v[200:203], v145 offset:39936
	global_load_lds_dwordx4 v172, s[26:27]
	s_mov_b32 m0, s37
	s_nop 0

	global_load_lds_dwordx4 v174, s[26:27]
	s_waitcnt lgkmcnt(8)
	s_barrier
	s_waitcnt lgkmcnt(0)


	v_mfma_f32_16x16x32_bf16 v[124:127], v[148:151], v[164:167], v[124:127]
	v_mfma_f32_16x16x32_bf16 v[120:123], v[156:159], v[164:167], v[120:123]
	v_mfma_f32_16x16x32_bf16 v[116:119], v[148:151], v[180:183], v[116:119]
	v_mfma_f32_16x16x32_bf16 v[104:107], v[156:159], v[180:183], v[104:107]
	v_mfma_f32_16x16x32_bf16 v[96:99], v[148:151], v[188:191], v[96:99]
	v_mfma_f32_16x16x32_bf16 v[88:91], v[156:159], v[188:191], v[88:91]
	v_mfma_f32_16x16x32_bf16 v[80:83], v[148:151], v[196:199], v[80:83]
	v_mfma_f32_16x16x32_bf16 v[72:75], v[156:159], v[196:199], v[72:75]
	v_mfma_f32_16x16x32_bf16 v[124:127], v[152:155], v[176:179], v[124:127]
	v_mfma_f32_16x16x32_bf16 v[120:123], v[160:163], v[176:179], v[120:123]
	v_mfma_f32_16x16x32_bf16 v[116:119], v[152:155], v[184:187], v[116:119]
	v_mfma_f32_16x16x32_bf16 v[104:107], v[160:163], v[184:187], v[104:107]
	v_mfma_f32_16x16x32_bf16 v[96:99], v[152:155], v[192:195], v[96:99]
	v_mfma_f32_16x16x32_bf16 v[88:91], v[160:163], v[192:195], v[88:91]
	v_mfma_f32_16x16x32_bf16 v[80:83], v[152:155], v[200:203], v[80:83]
	v_mfma_f32_16x16x32_bf16 v[72:75], v[160:163], v[200:203], v[72:75]

	s_barrier
	s_add_i32 s26, 0, 0x1c000
	s_add_i32 s27, s54, s31
	v_add_u32_e32 v138, s26, v139

	s_mov_b32 m0, s27
	ds_read_b128 v[204:207], v138
	ds_read_b128 v[218:221], v138 offset:1024
	ds_read_b128 v[222:225], v138 offset:2048
	ds_read_b128 v[226:229], v138 offset:3072
	global_load_lds_dwordx4 v172, s[66:67]
	s_add_i32 m0, s27, 0x2000
	s_nop 0

	global_load_lds_dwordx4 v174, s[66:67]
	s_barrier
	s_waitcnt lgkmcnt(0)


	v_mfma_f32_16x16x32_bf16 v[112:115], v[204:207], v[164:167], v[112:115]
	v_mfma_f32_16x16x32_bf16 v[108:111], v[222:225], v[164:167], v[108:111]
	v_mfma_f32_16x16x32_bf16 v[100:103], v[204:207], v[180:183], v[100:103]
	v_mfma_f32_16x16x32_bf16 v[92:95], v[222:225], v[180:183], v[92:95]
	v_mfma_f32_16x16x32_bf16 v[84:87], v[204:207], v[188:191], v[84:87]
	v_mfma_f32_16x16x32_bf16 v[76:79], v[222:225], v[188:191], v[76:79]
	v_mfma_f32_16x16x32_bf16 v[68:71], v[204:207], v[196:199], v[68:71]
	v_mfma_f32_16x16x32_bf16 v[64:67], v[222:225], v[196:199], v[64:67]
	v_mfma_f32_16x16x32_bf16 v[112:115], v[218:221], v[176:179], v[112:115]
	v_mfma_f32_16x16x32_bf16 v[108:111], v[226:229], v[176:179], v[108:111]
	v_mfma_f32_16x16x32_bf16 v[100:103], v[218:221], v[184:187], v[100:103]
	v_mfma_f32_16x16x32_bf16 v[92:95], v[226:229], v[184:187], v[92:95]
	v_mfma_f32_16x16x32_bf16 v[84:87], v[218:221], v[192:195], v[84:87]
	v_mfma_f32_16x16x32_bf16 v[76:79], v[226:229], v[192:195], v[76:79]
	v_mfma_f32_16x16x32_bf16 v[68:71], v[218:221], v[200:203], v[68:71]
	v_mfma_f32_16x16x32_bf16 v[64:67], v[226:229], v[200:203], v[64:67]

	s_mov_b32 m0, s41

	s_barrier
	ds_read_b128 v[164:167], v145 offset:49152
	ds_read_b128 v[176:179], v145 offset:50176
	ds_read_b128 v[180:183], v145 offset:51200
	ds_read_b128 v[184:187], v145 offset:52224
	ds_read_b128 v[188:191], v145 offset:53248
	ds_read_b128 v[192:195], v145 offset:54272
	ds_read_b128 v[196:199], v145 offset:55296
	ds_read_b128 v[200:203], v145 offset:56320
	global_load_lds_dwordx4 v172, s[68:69]
	s_mov_b32 m0, s42
	s_nop 0

	global_load_lds_dwordx4 v174, s[68:69]
	s_barrier
	s_waitcnt lgkmcnt(0)


	v_mfma_f32_16x16x32_bf16 v[60:63], v[148:151], v[164:167], v[60:63]
	v_mfma_f32_16x16x32_bf16 v[56:59], v[156:159], v[164:167], v[56:59]
	v_mfma_f32_16x16x32_bf16 v[48:51], v[148:151], v[180:183], v[48:51]
	v_mfma_f32_16x16x32_bf16 v[40:43], v[156:159], v[180:183], v[40:43]
	v_mfma_f32_16x16x32_bf16 v[32:35], v[148:151], v[188:191], v[32:35]
	v_mfma_f32_16x16x32_bf16 v[24:27], v[156:159], v[188:191], v[24:27]
	v_mfma_f32_16x16x32_bf16 v[16:19], v[148:151], v[196:199], v[16:19]
	v_mfma_f32_16x16x32_bf16 v[8:11], v[156:159], v[196:199], v[8:11]
	v_mfma_f32_16x16x32_bf16 v[60:63], v[152:155], v[176:179], v[60:63]
	v_mfma_f32_16x16x32_bf16 v[56:59], v[160:163], v[176:179], v[56:59]
	v_mfma_f32_16x16x32_bf16 v[48:51], v[152:155], v[184:187], v[48:51]
	v_mfma_f32_16x16x32_bf16 v[40:43], v[160:163], v[184:187], v[40:43]
	v_mfma_f32_16x16x32_bf16 v[32:35], v[152:155], v[192:195], v[32:35]
	v_mfma_f32_16x16x32_bf16 v[24:27], v[160:163], v[192:195], v[24:27]
	v_mfma_f32_16x16x32_bf16 v[16:19], v[152:155], v[200:203], v[16:19]
	v_mfma_f32_16x16x32_bf16 v[8:11], v[160:163], v[200:203], v[8:11]

	s_barrier
	s_add_u32 s24, s24, 0x80080
	s_addc_u32 s25, s25, 0
	s_add_i32 s26, s26, s31
	s_mov_b32 m0, s26
	s_nop 0

	global_load_lds_dwordx4 v172, s[24:25]
	s_add_i32 m0, s26, 0x2000
	s_nop 0

	global_load_lds_dwordx4 v174, s[24:25]
	s_waitcnt vmcnt(6)
	s_barrier

	v_mfma_f32_16x16x32_bf16 v[52:55], v[204:207], v[164:167], v[52:55]
	v_mfma_f32_16x16x32_bf16 v[44:47], v[222:225], v[164:167], v[44:47]
	v_mfma_f32_16x16x32_bf16 v[36:39], v[204:207], v[180:183], v[36:39]
	v_mfma_f32_16x16x32_bf16 v[28:31], v[222:225], v[180:183], v[28:31]
	v_mfma_f32_16x16x32_bf16 v[20:23], v[204:207], v[188:191], v[20:23]
	v_mfma_f32_16x16x32_bf16 v[12:15], v[222:225], v[188:191], v[12:15]
	v_mfma_f32_16x16x32_bf16 v[4:7], v[204:207], v[196:199], v[4:7]
	v_mfma_f32_16x16x32_bf16 v[0:3], v[222:225], v[196:199], v[0:3]
	v_mfma_f32_16x16x32_bf16 v[52:55], v[218:221], v[176:179], v[52:55]
	v_mfma_f32_16x16x32_bf16 v[44:47], v[226:229], v[176:179], v[44:47]
	v_mfma_f32_16x16x32_bf16 v[36:39], v[218:221], v[184:187], v[36:39]
	v_mfma_f32_16x16x32_bf16 v[28:31], v[226:229], v[184:187], v[28:31]
	v_mfma_f32_16x16x32_bf16 v[20:23], v[218:221], v[192:195], v[20:23]
	v_mfma_f32_16x16x32_bf16 v[12:15], v[226:229], v[192:195], v[12:15]
	v_mfma_f32_16x16x32_bf16 v[4:7], v[218:221], v[200:203], v[4:7]
	v_mfma_f32_16x16x32_bf16 v[0:3], v[226:229], v[200:203], v[0:3]

	s_add_i32 s53, s53, 2
	s_add_u32 s22, s22, 0x100
	s_addc_u32 s23, s23, 0
	s_add_u32 s51, s51, 0x100
	s_addc_u32 s52, s52, 0
	s_cmp_gt_u32 s53, 29
	s_barrier
	s_cbranch_scc0 .LBB0_1167
	s_lshl_b32 s13, s20, 8
	v_mov_b32_e32 v138, v210
	v_mov_b32_e32 v142, v169
	s_add_i32 s13, s13, s39
	s_lshl_b32 s15, s48, 7
	v_add_u32_e32 v136, s13, v142
	v_ashrrev_i32_e32 v137, 31, v136
	v_lshl_add_u64 v[140:141], v[136:137], 2, s[2:3]
	global_load_dword v154, v[140:141], off
	global_load_dword v152, v[140:141], off offset:64
	v_lshl_add_u32 v138, v138, 4, v142
	v_and_b32_e32 v142, 3, v142
	v_ashrrev_i32_e32 v144, 2, v138
	v_and_b32_e32 v138, -4, v138
	v_lshl_or_b32 v146, v142, 2, s15
	v_add_u32_e32 v151, s13, v144
	v_lshl_add_u32 v149, v142, 6, v138
	v_or_b32_e32 v156, s40, v146
	global_load_dword v150, v[140:141], off offset:128
	global_load_dword v148, v[140:141], off offset:192
	global_load_dword v146, v[140:141], off offset:512
	global_load_dword v144, v[140:141], off offset:576
	global_load_dword v142, v[140:141], off offset:640
	global_load_dword v138, v[140:141], off offset:704
	v_mov_b64_e32 v[136:137], s[0:1]
	v_ashrrev_i32_e32 v157, 31, v156
	v_mad_i64_i32 v[158:159], s[22:23], v151, s47, v[136:137]
	v_lshlrev_b64 v[140:141], 1, v[156:157]
	v_lshl_add_u64 v[156:157], v[158:159], 0, v[140:141]
	v_add_u32_e32 v153, 16, v151
	s_and_b64 vcc, exec, s[4:5]
	s_mov_b32 s48, s12
	s_mov_b32 s20, s14
	s_mov_b64 s[24:25], s[18:19]
	s_waitcnt vmcnt(0)
	v_pk_mul_f32 v[126:127], v[126:127], v[154:155] op_sel_hi:[1,0]
	v_pk_mul_f32 v[124:125], v[124:125], v[154:155] op_sel_hi:[1,0]
	v_pk_mul_f32 v[114:115], v[114:115], v[154:155] op_sel_hi:[1,0]
	v_pk_mul_f32 v[112:113], v[112:113], v[154:155] op_sel_hi:[1,0]
	v_pk_mul_f32 v[122:123], v[122:123], v[154:155] op_sel_hi:[1,0]
	v_pk_mul_f32 v[120:121], v[120:121], v[154:155] op_sel_hi:[1,0]
	v_pk_mul_f32 v[110:111], v[110:111], v[154:155] op_sel_hi:[1,0]
	v_pk_mul_f32 v[108:109], v[108:109], v[154:155] op_sel_hi:[1,0]
	v_mul_f32_e32 v154, 0xbfb8aa3b, v124
	v_mul_f32_e32 v155, 0xbfb8aa3b, v125
	v_mul_f32_e32 v158, 0xbfb8aa3b, v126
	v_mul_f32_e32 v159, 0xbfb8aa3b, v127
	v_mul_f32_e32 v160, 0xbfb8aa3b, v120
	v_mul_f32_e32 v161, 0xbfb8aa3b, v121
	v_mul_f32_e32 v162, 0xbfb8aa3b, v122
	v_mul_f32_e32 v163, 0xbfb8aa3b, v123
	v_exp_f32_e32 v154, v154
	v_exp_f32_e32 v155, v155
	v_exp_f32_e32 v158, v158
	v_exp_f32_e32 v159, v159
	v_exp_f32_e32 v160, v160
	v_exp_f32_e32 v161, v161
	v_exp_f32_e32 v162, v162
	v_exp_f32_e32 v163, v163
	v_add_f32_e32 v154, 1.0, v154
	v_add_f32_e32 v155, 1.0, v155
	v_add_f32_e32 v158, 1.0, v158
	v_add_f32_e32 v159, 1.0, v159
	v_add_f32_e32 v160, 1.0, v160
	v_add_f32_e32 v161, 1.0, v161
	v_add_f32_e32 v162, 1.0, v162
	v_add_f32_e32 v163, 1.0, v163
	v_rcp_f32_e32 v154, v154
	v_rcp_f32_e32 v155, v155
	v_rcp_f32_e32 v158, v158
	v_rcp_f32_e32 v159, v159
	v_rcp_f32_e32 v160, v160
	v_rcp_f32_e32 v161, v161
	v_rcp_f32_e32 v162, v162
	v_rcp_f32_e32 v163, v163
	v_pk_mul_f32 v[124:125], v[124:125], v[154:155]
	v_pk_mul_f32 v[126:127], v[126:127], v[158:159]
	v_pk_mul_f32 v[120:121], v[120:121], v[160:161]
	v_pk_mul_f32 v[122:123], v[122:123], v[162:163]
	v_pk_mul_f32 v[112:113], v[112:113], v[124:125]
	v_pk_mul_f32 v[114:115], v[114:115], v[126:127]
	v_pk_mul_f32 v[118:119], v[118:119], v[152:153] op_sel_hi:[1,0]
	v_pk_mul_f32 v[116:117], v[116:117], v[152:153] op_sel_hi:[1,0]
	v_pk_mul_f32 v[108:109], v[108:109], v[120:121]
	v_pk_mul_f32 v[110:111], v[110:111], v[122:123]
	v_cvt_pk_bf16_f32 v112, v112, v113
	v_cvt_pk_bf16_f32 v113, v114, v115
	v_mul_f32_e32 v164, 0xbfb8aa3b, v116
	v_mul_f32_e32 v165, 0xbfb8aa3b, v117
	v_mul_f32_e32 v166, 0xbfb8aa3b, v118
	v_mul_f32_e32 v167, 0xbfb8aa3b, v119
	v_cvt_pk_bf16_f32 v114, v108, v109
	v_cvt_pk_bf16_f32 v111, v110, v111
	ds_bpermute_b32 v108, v149, v112
	ds_bpermute_b32 v109, v149, v113
	v_exp_f32_e32 v164, v164
	v_exp_f32_e32 v165, v165
	v_exp_f32_e32 v166, v166
	v_exp_f32_e32 v167, v167
	ds_bpermute_b32 v110, v149, v114
	ds_bpermute_b32 v111, v149, v111
	v_add_f32_e32 v164, 1.0, v164
	v_add_f32_e32 v113, 1.0, v165
	s_waitcnt lgkmcnt(0)
	global_store_dwordx2 v[156:157], v[108:109], off
	global_store_dwordx2 v[156:157], v[110:111], off offset:32
	v_add_f32_e32 v108, 1.0, v166
	v_add_f32_e32 v109, 1.0, v167
	v_rcp_f32_e32 v112, v164
	v_rcp_f32_e32 v113, v113
	v_rcp_f32_e32 v108, v108
	v_rcp_f32_e32 v109, v109
	v_pk_mul_f32 v[102:103], v[102:103], v[152:153] op_sel_hi:[1,0]
	v_pk_mul_f32 v[100:101], v[100:101], v[152:153] op_sel_hi:[1,0]
	v_pk_mul_f32 v[110:111], v[116:117], v[112:113]
	v_pk_mul_f32 v[108:109], v[118:119], v[108:109]
	v_pk_mul_f32 v[100:101], v[100:101], v[110:111]
	v_pk_mul_f32 v[102:103], v[102:103], v[108:109]
	v_cvt_pk_bf16_f32 v100, v100, v101
	v_cvt_pk_bf16_f32 v101, v102, v103
	v_pk_mul_f32 v[102:103], v[106:107], v[152:153] op_sel_hi:[1,0]
	v_pk_mul_f32 v[104:105], v[104:105], v[152:153] op_sel_hi:[1,0]
	v_mul_f32_e32 v108, 0xbfb8aa3b, v102
	v_mul_f32_e32 v106, 0xbfb8aa3b, v104
	v_mul_f32_e32 v107, 0xbfb8aa3b, v105
	v_mul_f32_e32 v109, 0xbfb8aa3b, v103
	v_exp_f32_e32 v106, v106
	v_exp_f32_e32 v107, v107
	v_exp_f32_e32 v108, v108
	v_exp_f32_e32 v109, v109
	v_add_f32_e32 v106, 1.0, v106
	v_add_f32_e32 v107, 1.0, v107
	v_add_f32_e32 v108, 1.0, v108
	v_add_f32_e32 v109, 1.0, v109
	v_rcp_f32_e32 v106, v106
	v_rcp_f32_e32 v107, v107
	v_rcp_f32_e32 v108, v108
	v_rcp_f32_e32 v109, v109
	v_pk_mul_f32 v[94:95], v[94:95], v[152:153] op_sel_hi:[1,0]
	v_pk_mul_f32 v[92:93], v[92:93], v[152:153] op_sel_hi:[1,0]
	v_pk_mul_f32 v[104:105], v[104:105], v[106:107]
	v_pk_mul_f32 v[102:103], v[102:103], v[108:109]
	v_pk_mul_f32 v[92:93], v[92:93], v[104:105]
	v_pk_mul_f32 v[94:95], v[94:95], v[102:103]
	ds_bpermute_b32 v100, v149, v100
	ds_bpermute_b32 v101, v149, v101
	v_cvt_pk_bf16_f32 v92, v92, v93
	v_cvt_pk_bf16_f32 v93, v94, v95
	ds_bpermute_b32 v92, v149, v92
	ds_bpermute_b32 v93, v149, v93
	v_mad_i64_i32 v[94:95], s[22:23], v153, s47, v[136:137]
	v_lshl_add_u64 v[94:95], v[94:95], 0, v[140:141]
	s_waitcnt lgkmcnt(2)
	global_store_dwordx2 v[94:95], v[100:101], off
	s_waitcnt lgkmcnt(0)
	global_store_dwordx2 v[94:95], v[92:93], off offset:32
	v_pk_mul_f32 v[92:93], v[98:99], v[150:151] op_sel_hi:[1,0]
	v_pk_mul_f32 v[94:95], v[96:97], v[150:151] op_sel_hi:[1,0]
	v_mul_f32_e32 v98, 0xbfb8aa3b, v92
	v_mul_f32_e32 v96, 0xbfb8aa3b, v94
	v_mul_f32_e32 v97, 0xbfb8aa3b, v95
	v_mul_f32_e32 v99, 0xbfb8aa3b, v93
	v_exp_f32_e32 v96, v96
	v_exp_f32_e32 v97, v97
	v_exp_f32_e32 v98, v98
	v_exp_f32_e32 v99, v99
	v_add_f32_e32 v96, 1.0, v96
	v_add_f32_e32 v97, 1.0, v97
	v_add_f32_e32 v98, 1.0, v98
	v_add_f32_e32 v99, 1.0, v99
	v_rcp_f32_e32 v96, v96
	v_rcp_f32_e32 v97, v97
	v_rcp_f32_e32 v98, v98
	v_rcp_f32_e32 v99, v99
	v_pk_mul_f32 v[86:87], v[86:87], v[150:151] op_sel_hi:[1,0]
	v_pk_mul_f32 v[84:85], v[84:85], v[150:151] op_sel_hi:[1,0]
	v_pk_mul_f32 v[94:95], v[94:95], v[96:97]
	v_pk_mul_f32 v[92:93], v[92:93], v[98:99]
	v_pk_mul_f32 v[84:85], v[84:85], v[94:95]
	v_pk_mul_f32 v[86:87], v[86:87], v[92:93]
	v_cvt_pk_bf16_f32 v84, v84, v85
	v_cvt_pk_bf16_f32 v85, v86, v87
	v_pk_mul_f32 v[86:87], v[90:91], v[150:151] op_sel_hi:[1,0]
	v_pk_mul_f32 v[88:89], v[88:89], v[150:151] op_sel_hi:[1,0]
	v_mul_f32_e32 v92, 0xbfb8aa3b, v86
	v_mul_f32_e32 v90, 0xbfb8aa3b, v88
	v_mul_f32_e32 v91, 0xbfb8aa3b, v89
	v_mul_f32_e32 v93, 0xbfb8aa3b, v87
	v_exp_f32_e32 v90, v90
	v_exp_f32_e32 v91, v91
	v_exp_f32_e32 v92, v92
	v_exp_f32_e32 v93, v93
	v_add_f32_e32 v90, 1.0, v90
	v_add_f32_e32 v91, 1.0, v91
	v_add_f32_e32 v92, 1.0, v92
	v_add_f32_e32 v93, 1.0, v93
	v_rcp_f32_e32 v90, v90
	v_rcp_f32_e32 v91, v91
	v_rcp_f32_e32 v92, v92
	v_rcp_f32_e32 v93, v93
	v_pk_mul_f32 v[78:79], v[78:79], v[150:151] op_sel_hi:[1,0]
	v_pk_mul_f32 v[76:77], v[76:77], v[150:151] op_sel_hi:[1,0]
	v_pk_mul_f32 v[88:89], v[88:89], v[90:91]
	v_pk_mul_f32 v[86:87], v[86:87], v[92:93]
	v_pk_mul_f32 v[76:77], v[76:77], v[88:89]
	v_pk_mul_f32 v[78:79], v[78:79], v[86:87]
	ds_bpermute_b32 v84, v149, v84
	ds_bpermute_b32 v85, v149, v85
	v_cvt_pk_bf16_f32 v76, v76, v77
	v_cvt_pk_bf16_f32 v77, v78, v79
	ds_bpermute_b32 v76, v149, v76
	ds_bpermute_b32 v77, v149, v77
	v_add_u32_e32 v100, 32, v151
	v_mad_i64_i32 v[78:79], s[22:23], v100, s47, v[136:137]
	v_lshl_add_u64 v[78:79], v[78:79], 0, v[140:141]
	s_waitcnt lgkmcnt(2)
	global_store_dwordx2 v[78:79], v[84:85], off
	s_waitcnt lgkmcnt(0)
	global_store_dwordx2 v[78:79], v[76:77], off offset:32
	v_pk_mul_f32 v[76:77], v[82:83], v[148:149] op_sel_hi:[1,0]
	v_pk_mul_f32 v[78:79], v[80:81], v[148:149] op_sel_hi:[1,0]
	v_mul_f32_e32 v82, 0xbfb8aa3b, v76
	v_mul_f32_e32 v80, 0xbfb8aa3b, v78
	v_mul_f32_e32 v81, 0xbfb8aa3b, v79
	v_mul_f32_e32 v83, 0xbfb8aa3b, v77
	v_exp_f32_e32 v80, v80
	v_exp_f32_e32 v81, v81
	v_exp_f32_e32 v82, v82
	v_exp_f32_e32 v83, v83
	v_add_f32_e32 v80, 1.0, v80
	v_add_f32_e32 v81, 1.0, v81
	v_add_f32_e32 v82, 1.0, v82
	v_add_f32_e32 v83, 1.0, v83
	v_rcp_f32_e32 v80, v80
	v_rcp_f32_e32 v81, v81
	v_rcp_f32_e32 v82, v82
	v_rcp_f32_e32 v83, v83
	v_pk_mul_f32 v[70:71], v[70:71], v[148:149] op_sel_hi:[1,0]
	v_pk_mul_f32 v[68:69], v[68:69], v[148:149] op_sel_hi:[1,0]
	v_pk_mul_f32 v[78:79], v[78:79], v[80:81]
	v_pk_mul_f32 v[76:77], v[76:77], v[82:83]
	v_pk_mul_f32 v[68:69], v[68:69], v[78:79]
	v_pk_mul_f32 v[70:71], v[70:71], v[76:77]
	v_cvt_pk_bf16_f32 v68, v68, v69
	v_cvt_pk_bf16_f32 v69, v70, v71
	v_pk_mul_f32 v[70:71], v[74:75], v[148:149] op_sel_hi:[1,0]
	v_pk_mul_f32 v[72:73], v[72:73], v[148:149] op_sel_hi:[1,0]
	v_mul_f32_e32 v76, 0xbfb8aa3b, v70
	v_mul_f32_e32 v74, 0xbfb8aa3b, v72
	v_mul_f32_e32 v75, 0xbfb8aa3b, v73
	v_mul_f32_e32 v77, 0xbfb8aa3b, v71
	v_exp_f32_e32 v74, v74
	v_exp_f32_e32 v75, v75
	v_exp_f32_e32 v76, v76
	v_exp_f32_e32 v77, v77
	v_add_f32_e32 v74, 1.0, v74
	v_add_f32_e32 v75, 1.0, v75
	v_add_f32_e32 v76, 1.0, v76
	v_add_f32_e32 v77, 1.0, v77
	v_rcp_f32_e32 v74, v74
	v_rcp_f32_e32 v75, v75
	v_rcp_f32_e32 v76, v76
	v_rcp_f32_e32 v77, v77
	v_pk_mul_f32 v[66:67], v[66:67], v[148:149] op_sel_hi:[1,0]
	v_pk_mul_f32 v[64:65], v[64:65], v[148:149] op_sel_hi:[1,0]
	v_pk_mul_f32 v[72:73], v[72:73], v[74:75]
	v_pk_mul_f32 v[70:71], v[70:71], v[76:77]
	v_pk_mul_f32 v[64:65], v[64:65], v[72:73]
	v_pk_mul_f32 v[66:67], v[66:67], v[70:71]
	ds_bpermute_b32 v68, v149, v68
	ds_bpermute_b32 v69, v149, v69
	v_cvt_pk_bf16_f32 v64, v64, v65
	v_cvt_pk_bf16_f32 v65, v66, v67
	ds_bpermute_b32 v64, v149, v64
	ds_bpermute_b32 v65, v149, v65
	v_add_u32_e32 v84, 48, v151
	v_mad_i64_i32 v[66:67], s[22:23], v84, s47, v[136:137]
	v_lshl_add_u64 v[66:67], v[66:67], 0, v[140:141]
	v_pk_mul_f32 v[60:61], v[60:61], v[146:147] op_sel_hi:[1,0]
	s_waitcnt lgkmcnt(2)
	global_store_dwordx2 v[66:67], v[68:69], off
	s_waitcnt lgkmcnt(0)
	global_store_dwordx2 v[66:67], v[64:65], off offset:32
	v_pk_mul_f32 v[62:63], v[62:63], v[146:147] op_sel_hi:[1,0]
	v_mul_f32_e32 v64, 0xbfb8aa3b, v60
	v_mul_f32_e32 v65, 0xbfb8aa3b, v61
	v_exp_f32_e32 v64, v64
	v_exp_f32_e32 v65, v65
	v_mul_f32_e32 v66, 0xbfb8aa3b, v62
	v_mul_f32_e32 v67, 0xbfb8aa3b, v63
	v_exp_f32_e32 v66, v66
	v_exp_f32_e32 v67, v67
	v_add_f32_e32 v64, 1.0, v64
	v_add_f32_e32 v65, 1.0, v65
	v_rcp_f32_e32 v64, v64
	v_rcp_f32_e32 v65, v65
	v_add_f32_e32 v66, 1.0, v66
	v_add_f32_e32 v67, 1.0, v67
	v_rcp_f32_e32 v66, v66
	v_rcp_f32_e32 v67, v67
	v_pk_mul_f32 v[52:53], v[52:53], v[146:147] op_sel_hi:[1,0]
	v_pk_mul_f32 v[60:61], v[60:61], v[64:65]
	v_pk_mul_f32 v[54:55], v[54:55], v[146:147] op_sel_hi:[1,0]
	v_pk_mul_f32 v[52:53], v[52:53], v[60:61]
	v_pk_mul_f32 v[60:61], v[62:63], v[66:67]
	v_cvt_pk_bf16_f32 v52, v52, v53
	v_pk_mul_f32 v[54:55], v[54:55], v[60:61]
	v_pk_mul_f32 v[56:57], v[56:57], v[146:147] op_sel_hi:[1,0]
	v_cvt_pk_bf16_f32 v53, v54, v55
	v_pk_mul_f32 v[54:55], v[58:59], v[146:147] op_sel_hi:[1,0]
	v_mul_f32_e32 v58, 0xbfb8aa3b, v56
	v_mul_f32_e32 v59, 0xbfb8aa3b, v57
	v_mul_f32_e32 v60, 0xbfb8aa3b, v54
	v_mul_f32_e32 v61, 0xbfb8aa3b, v55
	v_exp_f32_e32 v58, v58
	v_exp_f32_e32 v59, v59
	v_exp_f32_e32 v60, v60
	v_exp_f32_e32 v61, v61
	v_add_f32_e32 v58, 1.0, v58
	v_add_f32_e32 v59, 1.0, v59
	v_add_f32_e32 v60, 1.0, v60
	v_add_f32_e32 v61, 1.0, v61
	v_rcp_f32_e32 v58, v58
	v_rcp_f32_e32 v59, v59
	v_rcp_f32_e32 v60, v60
	v_rcp_f32_e32 v61, v61
	v_pk_mul_f32 v[46:47], v[46:47], v[146:147] op_sel_hi:[1,0]
	v_pk_mul_f32 v[44:45], v[44:45], v[146:147] op_sel_hi:[1,0]
	v_pk_mul_f32 v[56:57], v[56:57], v[58:59]
	v_pk_mul_f32 v[54:55], v[54:55], v[60:61]
	v_pk_mul_f32 v[44:45], v[44:45], v[56:57]
	v_pk_mul_f32 v[46:47], v[46:47], v[54:55]
	ds_bpermute_b32 v52, v149, v52
	ds_bpermute_b32 v53, v149, v53
	v_cvt_pk_bf16_f32 v44, v44, v45
	v_cvt_pk_bf16_f32 v45, v46, v47
	ds_bpermute_b32 v44, v149, v44
	ds_bpermute_b32 v45, v149, v45
	v_add_u32_e32 v68, 0x80, v151
	v_mad_i64_i32 v[46:47], s[22:23], v68, s47, v[136:137]
	v_lshl_add_u64 v[46:47], v[46:47], 0, v[140:141]
	s_waitcnt lgkmcnt(2)
	global_store_dwordx2 v[46:47], v[52:53], off
	s_waitcnt lgkmcnt(0)
	global_store_dwordx2 v[46:47], v[44:45], off offset:32
	v_pk_mul_f32 v[44:45], v[50:51], v[144:145] op_sel_hi:[1,0]
	v_pk_mul_f32 v[46:47], v[48:49], v[144:145] op_sel_hi:[1,0]
	v_mul_f32_e32 v50, 0xbfb8aa3b, v44
	v_mul_f32_e32 v48, 0xbfb8aa3b, v46
	v_mul_f32_e32 v49, 0xbfb8aa3b, v47
	v_mul_f32_e32 v51, 0xbfb8aa3b, v45
	v_exp_f32_e32 v48, v48
	v_exp_f32_e32 v49, v49
	v_exp_f32_e32 v50, v50
	v_exp_f32_e32 v51, v51
	v_add_f32_e32 v48, 1.0, v48
	v_add_f32_e32 v49, 1.0, v49
	v_add_f32_e32 v50, 1.0, v50
	v_add_f32_e32 v51, 1.0, v51
	v_rcp_f32_e32 v48, v48
	v_rcp_f32_e32 v49, v49
	v_rcp_f32_e32 v50, v50
	v_rcp_f32_e32 v51, v51
	v_pk_mul_f32 v[38:39], v[38:39], v[144:145] op_sel_hi:[1,0]
	v_pk_mul_f32 v[36:37], v[36:37], v[144:145] op_sel_hi:[1,0]
	v_pk_mul_f32 v[46:47], v[46:47], v[48:49]
	v_pk_mul_f32 v[44:45], v[44:45], v[50:51]
	v_pk_mul_f32 v[36:37], v[36:37], v[46:47]
	v_pk_mul_f32 v[38:39], v[38:39], v[44:45]
	v_cvt_pk_bf16_f32 v36, v36, v37
	v_cvt_pk_bf16_f32 v37, v38, v39
	v_pk_mul_f32 v[38:39], v[42:43], v[144:145] op_sel_hi:[1,0]
	v_pk_mul_f32 v[40:41], v[40:41], v[144:145] op_sel_hi:[1,0]
	v_mul_f32_e32 v44, 0xbfb8aa3b, v38
	v_mul_f32_e32 v42, 0xbfb8aa3b, v40
	v_mul_f32_e32 v43, 0xbfb8aa3b, v41
	v_mul_f32_e32 v45, 0xbfb8aa3b, v39
	v_exp_f32_e32 v42, v42
	v_exp_f32_e32 v43, v43
	v_exp_f32_e32 v44, v44
	v_exp_f32_e32 v45, v45
	v_add_f32_e32 v42, 1.0, v42
	v_add_f32_e32 v43, 1.0, v43
	v_add_f32_e32 v44, 1.0, v44
	v_add_f32_e32 v45, 1.0, v45
	v_rcp_f32_e32 v42, v42
	v_rcp_f32_e32 v43, v43
	v_rcp_f32_e32 v44, v44
	v_rcp_f32_e32 v45, v45
	v_pk_mul_f32 v[30:31], v[30:31], v[144:145] op_sel_hi:[1,0]
	v_pk_mul_f32 v[28:29], v[28:29], v[144:145] op_sel_hi:[1,0]
	v_pk_mul_f32 v[40:41], v[40:41], v[42:43]
	v_pk_mul_f32 v[38:39], v[38:39], v[44:45]
	v_pk_mul_f32 v[28:29], v[28:29], v[40:41]
	v_pk_mul_f32 v[30:31], v[30:31], v[38:39]
	ds_bpermute_b32 v36, v149, v36
	ds_bpermute_b32 v37, v149, v37
	v_cvt_pk_bf16_f32 v28, v28, v29
	v_cvt_pk_bf16_f32 v29, v30, v31
	ds_bpermute_b32 v28, v149, v28
	ds_bpermute_b32 v29, v149, v29
	v_add_u32_e32 v52, 0x90, v151
	v_mad_i64_i32 v[30:31], s[22:23], v52, s47, v[136:137]
	v_lshl_add_u64 v[30:31], v[30:31], 0, v[140:141]
	s_waitcnt lgkmcnt(2)
	global_store_dwordx2 v[30:31], v[36:37], off
	s_waitcnt lgkmcnt(0)
	global_store_dwordx2 v[30:31], v[28:29], off offset:32
	v_pk_mul_f32 v[28:29], v[34:35], v[142:143] op_sel_hi:[1,0]
	v_pk_mul_f32 v[30:31], v[32:33], v[142:143] op_sel_hi:[1,0]
	v_mul_f32_e32 v34, 0xbfb8aa3b, v28
	v_mul_f32_e32 v32, 0xbfb8aa3b, v30
	v_mul_f32_e32 v33, 0xbfb8aa3b, v31
	v_mul_f32_e32 v35, 0xbfb8aa3b, v29
	v_exp_f32_e32 v32, v32
	v_exp_f32_e32 v33, v33
	v_exp_f32_e32 v34, v34
	v_exp_f32_e32 v35, v35
	v_add_f32_e32 v32, 1.0, v32
	v_add_f32_e32 v33, 1.0, v33
	v_add_f32_e32 v34, 1.0, v34
	v_add_f32_e32 v35, 1.0, v35
	v_rcp_f32_e32 v32, v32
	v_rcp_f32_e32 v33, v33
	v_rcp_f32_e32 v34, v34
	v_rcp_f32_e32 v35, v35
	v_pk_mul_f32 v[22:23], v[22:23], v[142:143] op_sel_hi:[1,0]
	v_pk_mul_f32 v[20:21], v[20:21], v[142:143] op_sel_hi:[1,0]
	v_pk_mul_f32 v[30:31], v[30:31], v[32:33]
	v_pk_mul_f32 v[28:29], v[28:29], v[34:35]
	v_pk_mul_f32 v[20:21], v[20:21], v[30:31]
	v_pk_mul_f32 v[22:23], v[22:23], v[28:29]
	v_cvt_pk_bf16_f32 v20, v20, v21
	v_cvt_pk_bf16_f32 v21, v22, v23
	v_pk_mul_f32 v[22:23], v[26:27], v[142:143] op_sel_hi:[1,0]
	v_pk_mul_f32 v[24:25], v[24:25], v[142:143] op_sel_hi:[1,0]
	v_mul_f32_e32 v28, 0xbfb8aa3b, v22
	v_mul_f32_e32 v26, 0xbfb8aa3b, v24
	v_mul_f32_e32 v27, 0xbfb8aa3b, v25
	v_mul_f32_e32 v29, 0xbfb8aa3b, v23
	v_exp_f32_e32 v26, v26
	v_exp_f32_e32 v27, v27
	v_exp_f32_e32 v28, v28
	v_exp_f32_e32 v29, v29
	v_add_f32_e32 v26, 1.0, v26
	v_add_f32_e32 v27, 1.0, v27
	v_add_f32_e32 v28, 1.0, v28
	v_add_f32_e32 v29, 1.0, v29
	v_rcp_f32_e32 v26, v26
	v_rcp_f32_e32 v27, v27
	v_rcp_f32_e32 v28, v28
	v_rcp_f32_e32 v29, v29
	v_pk_mul_f32 v[14:15], v[14:15], v[142:143] op_sel_hi:[1,0]
	v_pk_mul_f32 v[12:13], v[12:13], v[142:143] op_sel_hi:[1,0]
	v_pk_mul_f32 v[24:25], v[24:25], v[26:27]
	v_pk_mul_f32 v[22:23], v[22:23], v[28:29]
	v_pk_mul_f32 v[12:13], v[12:13], v[24:25]
	v_pk_mul_f32 v[14:15], v[14:15], v[22:23]
	ds_bpermute_b32 v20, v149, v20
	ds_bpermute_b32 v21, v149, v21
	v_cvt_pk_bf16_f32 v12, v12, v13
	v_cvt_pk_bf16_f32 v13, v14, v15
	ds_bpermute_b32 v12, v149, v12
	ds_bpermute_b32 v13, v149, v13
	v_add_u32_e32 v36, 0xa0, v151
	v_mad_i64_i32 v[14:15], s[22:23], v36, s47, v[136:137]
	v_lshl_add_u64 v[14:15], v[14:15], 0, v[140:141]
	s_waitcnt lgkmcnt(2)
	global_store_dwordx2 v[14:15], v[20:21], off
	s_waitcnt lgkmcnt(0)
	global_store_dwordx2 v[14:15], v[12:13], off offset:32
	v_pk_mul_f32 v[12:13], v[18:19], v[138:139] op_sel_hi:[1,0]
	v_pk_mul_f32 v[14:15], v[16:17], v[138:139] op_sel_hi:[1,0]
	v_mul_f32_e32 v18, 0xbfb8aa3b, v12
	v_mul_f32_e32 v16, 0xbfb8aa3b, v14
	v_mul_f32_e32 v17, 0xbfb8aa3b, v15
	v_mul_f32_e32 v19, 0xbfb8aa3b, v13
	v_exp_f32_e32 v16, v16
	v_exp_f32_e32 v17, v17
	v_exp_f32_e32 v18, v18
	v_exp_f32_e32 v19, v19
	v_add_f32_e32 v16, 1.0, v16
	v_add_f32_e32 v17, 1.0, v17
	v_add_f32_e32 v18, 1.0, v18
	v_add_f32_e32 v19, 1.0, v19
	v_rcp_f32_e32 v16, v16
	v_rcp_f32_e32 v17, v17
	v_rcp_f32_e32 v18, v18
	v_rcp_f32_e32 v19, v19
	v_pk_mul_f32 v[6:7], v[6:7], v[138:139] op_sel_hi:[1,0]
	v_pk_mul_f32 v[4:5], v[4:5], v[138:139] op_sel_hi:[1,0]
	v_pk_mul_f32 v[14:15], v[14:15], v[16:17]
	v_pk_mul_f32 v[12:13], v[12:13], v[18:19]
	v_pk_mul_f32 v[4:5], v[4:5], v[14:15]
	v_pk_mul_f32 v[6:7], v[6:7], v[12:13]
	v_cvt_pk_bf16_f32 v4, v4, v5
	v_cvt_pk_bf16_f32 v5, v6, v7
	v_pk_mul_f32 v[6:7], v[10:11], v[138:139] op_sel_hi:[1,0]
	v_pk_mul_f32 v[8:9], v[8:9], v[138:139] op_sel_hi:[1,0]
	v_mul_f32_e32 v12, 0xbfb8aa3b, v6
	v_mul_f32_e32 v10, 0xbfb8aa3b, v8
	v_mul_f32_e32 v11, 0xbfb8aa3b, v9
	v_mul_f32_e32 v13, 0xbfb8aa3b, v7
	v_exp_f32_e32 v10, v10
	v_exp_f32_e32 v11, v11
	v_exp_f32_e32 v12, v12
	v_exp_f32_e32 v13, v13
	v_add_f32_e32 v10, 1.0, v10
	v_add_f32_e32 v11, 1.0, v11
	v_add_f32_e32 v12, 1.0, v12
	v_add_f32_e32 v13, 1.0, v13
	v_rcp_f32_e32 v10, v10
	v_rcp_f32_e32 v11, v11
	v_rcp_f32_e32 v12, v12
	v_rcp_f32_e32 v13, v13
	v_pk_mul_f32 v[2:3], v[2:3], v[138:139] op_sel_hi:[1,0]
	v_pk_mul_f32 v[0:1], v[0:1], v[138:139] op_sel_hi:[1,0]
	v_pk_mul_f32 v[8:9], v[8:9], v[10:11]
	v_pk_mul_f32 v[6:7], v[6:7], v[12:13]
	v_pk_mul_f32 v[0:1], v[0:1], v[8:9]
	v_pk_mul_f32 v[2:3], v[2:3], v[6:7]
	ds_bpermute_b32 v4, v149, v4
	ds_bpermute_b32 v5, v149, v5
	v_cvt_pk_bf16_f32 v0, v0, v1
	v_cvt_pk_bf16_f32 v1, v2, v3
	ds_bpermute_b32 v0, v149, v0
	ds_bpermute_b32 v1, v149, v1
	v_add_u32_e32 v20, 0xb0, v151
	v_mad_i64_i32 v[2:3], s[22:23], v20, s47, v[136:137]
	v_lshl_add_u64 v[2:3], v[2:3], 0, v[140:141]
	s_mov_b64 s[22:23], s[16:17]
	s_waitcnt lgkmcnt(2)
	global_store_dwordx2 v[2:3], v[4:5], off
	s_waitcnt lgkmcnt(0)
	global_store_dwordx2 v[2:3], v[0:1], off offset:32
	s_cbranch_vccz .LBB0_1164
	s_waitcnt vmcnt(0)
	s_cmpk_gt_u32 s28, 0xff
	s_cbranch_scc1 .LBB0_1171
	s_barrier

.LBB0_1258:
	ds_read_b128 v[128:131], v159
	ds_read_b128 v[132:135], v159 offset:1024
	ds_read_b128 v[136:139], v159 offset:2048
	ds_read_b128 v[150:153], v159 offset:3072
	s_add_i32 s54, s18, 2
	s_add_u32 s19, s16, 0xffea0080
	s_addc_u32 s20, s17, -1
	s_cmp_eq_u32 s13, s18
	s_cselect_b32 s18, s4, s52
	s_cselect_b32 s21, s15, s20
	s_cselect_b32 s20, s14, s19
	s_cselect_b32 s19, s5, s53

	s_add_i32 m0, s26, 0xc000
	ds_read_b128 v[154:157], v160
	ds_read_b128 v[162:165], v160 offset:1024
	ds_read_b128 v[172:175], v160 offset:2048
	ds_read_b128 v[176:179], v160 offset:3072
	ds_read_b128 v[180:183], v160 offset:4096
	ds_read_b128 v[184:187], v160 offset:5120
	ds_read_b128 v[188:191], v160 offset:6144
	ds_read_b128 v[192:195], v160 offset:7168
	global_load_lds_dwordx4 v146, s[16:17]
	s_add_i32 m0, s26, 0xe000
	s_nop 0

	global_load_lds_dwordx4 v148, s[16:17]
	s_waitcnt lgkmcnt(8)
	s_barrier
	s_waitcnt lgkmcnt(0)


	v_mfma_f32_16x16x32_bf16 v[124:127], v[128:131], v[154:157], v[124:127]
	v_mfma_f32_16x16x32_bf16 v[120:123], v[136:139], v[154:157], v[120:123]
	v_mfma_f32_16x16x32_bf16 v[116:119], v[128:131], v[172:175], v[116:119]
	v_mfma_f32_16x16x32_bf16 v[104:107], v[136:139], v[172:175], v[104:107]
	v_mfma_f32_16x16x32_bf16 v[96:99], v[128:131], v[180:183], v[96:99]
	v_mfma_f32_16x16x32_bf16 v[88:91], v[136:139], v[180:183], v[88:91]
	v_mfma_f32_16x16x32_bf16 v[80:83], v[128:131], v[188:191], v[80:83]
	v_mfma_f32_16x16x32_bf16 v[72:75], v[136:139], v[188:191], v[72:75]
	v_mfma_f32_16x16x32_bf16 v[124:127], v[132:135], v[162:165], v[124:127]
	v_mfma_f32_16x16x32_bf16 v[120:123], v[150:153], v[162:165], v[120:123]
	v_mfma_f32_16x16x32_bf16 v[116:119], v[132:135], v[176:179], v[116:119]
	v_mfma_f32_16x16x32_bf16 v[104:107], v[150:153], v[176:179], v[104:107]
	v_mfma_f32_16x16x32_bf16 v[96:99], v[132:135], v[184:187], v[96:99]
	v_mfma_f32_16x16x32_bf16 v[88:91], v[150:153], v[184:187], v[88:91]
	v_mfma_f32_16x16x32_bf16 v[80:83], v[132:135], v[192:195], v[80:83]
	v_mfma_f32_16x16x32_bf16 v[72:75], v[150:153], v[192:195], v[72:75]

	s_barrier
	s_add_i32 s55, s35, s25
	s_add_u32 s66, s18, s6
	s_addc_u32 s67, s19, s7
	s_mov_b32 m0, s55
	ds_read_b128 v[196:199], v161
	ds_read_b128 v[200:203], v161 offset:1024
	ds_read_b128 v[204:207], v161 offset:2048
	ds_read_b128 v[212:215], v161 offset:3072
	global_load_lds_dwordx4 v140, s[18:19]
	s_add_i32 m0, s55, 0x2000
	s_nop 0

	global_load_lds_dwordx4 v142, s[18:19]
	s_barrier
	s_waitcnt lgkmcnt(0)


	v_mfma_f32_16x16x32_bf16 v[112:115], v[196:199], v[154:157], v[112:115]
	v_mfma_f32_16x16x32_bf16 v[108:111], v[204:207], v[154:157], v[108:111]
	v_mfma_f32_16x16x32_bf16 v[100:103], v[196:199], v[172:175], v[100:103]
	v_mfma_f32_16x16x32_bf16 v[92:95], v[204:207], v[172:175], v[92:95]
	v_mfma_f32_16x16x32_bf16 v[84:87], v[196:199], v[180:183], v[84:87]
	v_mfma_f32_16x16x32_bf16 v[76:79], v[204:207], v[180:183], v[76:79]
	v_mfma_f32_16x16x32_bf16 v[68:71], v[196:199], v[188:191], v[68:71]
	v_mfma_f32_16x16x32_bf16 v[64:67], v[204:207], v[188:191], v[64:67]
	v_mfma_f32_16x16x32_bf16 v[112:115], v[200:203], v[162:165], v[112:115]
	v_mfma_f32_16x16x32_bf16 v[108:111], v[212:215], v[162:165], v[108:111]
	v_mfma_f32_16x16x32_bf16 v[100:103], v[200:203], v[176:179], v[100:103]
	v_mfma_f32_16x16x32_bf16 v[92:95], v[212:215], v[176:179], v[92:95]
	v_mfma_f32_16x16x32_bf16 v[84:87], v[200:203], v[184:187], v[84:87]
	v_mfma_f32_16x16x32_bf16 v[76:79], v[212:215], v[184:187], v[76:79]
	v_mfma_f32_16x16x32_bf16 v[68:71], v[200:203], v[192:195], v[68:71]
	v_mfma_f32_16x16x32_bf16 v[64:67], v[212:215], v[192:195], v[64:67]

	s_mov_b32 m0, s26
	s_add_u32 s68, s20, s6
	s_addc_u32 s69, s21, s7
	s_barrier
	ds_read_b128 v[154:157], v160 offset:16384
	ds_read_b128 v[162:165], v160 offset:17408
	ds_read_b128 v[172:175], v160 offset:18432
	ds_read_b128 v[176:179], v160 offset:19456
	ds_read_b128 v[180:183], v160 offset:20480
	ds_read_b128 v[184:187], v160 offset:21504
	ds_read_b128 v[188:191], v160 offset:22528
	ds_read_b128 v[192:195], v160 offset:23552
	global_load_lds_dwordx4 v140, s[20:21]
	s_mov_b32 m0, s27
	s_nop 0

	global_load_lds_dwordx4 v142, s[20:21]
	s_barrier
	s_waitcnt lgkmcnt(0)


	v_mfma_f32_16x16x32_bf16 v[60:63], v[128:131], v[154:157], v[60:63]
	v_mfma_f32_16x16x32_bf16 v[56:59], v[136:139], v[154:157], v[56:59]
	v_mfma_f32_16x16x32_bf16 v[52:55], v[128:131], v[172:175], v[52:55]
	v_mfma_f32_16x16x32_bf16 v[40:43], v[136:139], v[172:175], v[40:43]
	v_mfma_f32_16x16x32_bf16 v[36:39], v[128:131], v[180:183], v[36:39]
	v_mfma_f32_16x16x32_bf16 v[24:27], v[136:139], v[180:183], v[24:27]
	v_mfma_f32_16x16x32_bf16 v[20:23], v[128:131], v[188:191], v[20:23]
	v_mfma_f32_16x16x32_bf16 v[8:11], v[136:139], v[188:191], v[8:11]
	v_mfma_f32_16x16x32_bf16 v[60:63], v[132:135], v[162:165], v[60:63]
	v_mfma_f32_16x16x32_bf16 v[56:59], v[150:153], v[162:165], v[56:59]
	v_mfma_f32_16x16x32_bf16 v[52:55], v[132:135], v[176:179], v[52:55]
	v_mfma_f32_16x16x32_bf16 v[40:43], v[150:153], v[176:179], v[40:43]
	v_mfma_f32_16x16x32_bf16 v[36:39], v[132:135], v[184:187], v[36:39]
	v_mfma_f32_16x16x32_bf16 v[24:27], v[150:153], v[184:187], v[24:27]
	v_mfma_f32_16x16x32_bf16 v[20:23], v[132:135], v[192:195], v[20:23]
	v_mfma_f32_16x16x32_bf16 v[8:11], v[150:153], v[192:195], v[8:11]

	s_barrier
	s_add_u32 s56, s18, 0x160000
	s_addc_u32 s57, s19, 0
	s_add_i32 s55, s36, s25
	s_mov_b32 m0, s55
	s_nop 0

	global_load_lds_dwordx4 v140, s[56:57]
	s_add_i32 m0, s55, 0x2000
	s_nop 0

	global_load_lds_dwordx4 v142, s[56:57]
	s_waitcnt vmcnt(6)
	s_barrier

	v_mfma_f32_16x16x32_bf16 v[48:51], v[196:199], v[154:157], v[48:51]
	v_mfma_f32_16x16x32_bf16 v[44:47], v[204:207], v[154:157], v[44:47]
	v_mfma_f32_16x16x32_bf16 v[32:35], v[196:199], v[172:175], v[32:35]
	v_mfma_f32_16x16x32_bf16 v[28:31], v[204:207], v[172:175], v[28:31]
	v_mfma_f32_16x16x32_bf16 v[16:19], v[196:199], v[180:183], v[16:19]
	v_mfma_f32_16x16x32_bf16 v[12:15], v[204:207], v[180:183], v[12:15]
	v_mfma_f32_16x16x32_bf16 v[4:7], v[196:199], v[188:191], v[4:7]
	v_mfma_f32_16x16x32_bf16 v[0:3], v[204:207], v[188:191], v[0:3]
	v_mfma_f32_16x16x32_bf16 v[48:51], v[200:203], v[162:165], v[48:51]
	v_mfma_f32_16x16x32_bf16 v[44:47], v[212:215], v[162:165], v[44:47]
	v_mfma_f32_16x16x32_bf16 v[32:35], v[200:203], v[176:179], v[32:35]
	v_mfma_f32_16x16x32_bf16 v[28:31], v[212:215], v[176:179], v[28:31]
	v_mfma_f32_16x16x32_bf16 v[16:19], v[200:203], v[184:187], v[16:19]
	v_mfma_f32_16x16x32_bf16 v[12:15], v[212:215], v[184:187], v[12:15]
	v_mfma_f32_16x16x32_bf16 v[4:7], v[200:203], v[192:195], v[4:7]
	v_mfma_f32_16x16x32_bf16 v[0:3], v[212:215], v[192:195], v[0:3]

	s_add_i32 s55, 0, 0x18000
	v_add_u32_e32 v144, s55, v158
	s_barrier
	ds_read_b128 v[128:131], v144
	ds_read_b128 v[132:135], v144 offset:1024
	ds_read_b128 v[136:139], v144 offset:2048
	ds_read_b128 v[150:153], v144 offset:3072
	s_add_u32 s20, s20, 0x160000
	s_addc_u32 s21, s21, 0
	s_mov_b32 m0, s28

	ds_read_b128 v[154:157], v160 offset:32768
	ds_read_b128 v[162:165], v160 offset:33792
	ds_read_b128 v[172:175], v160 offset:34816
	ds_read_b128 v[176:179], v160 offset:35840
	ds_read_b128 v[180:183], v160 offset:36864
	ds_read_b128 v[184:187], v160 offset:37888
	ds_read_b128 v[188:191], v160 offset:38912
	ds_read_b128 v[192:195], v160 offset:39936
	global_load_lds_dwordx4 v140, s[20:21]
	s_mov_b32 m0, s29
	s_nop 0

	global_load_lds_dwordx4 v142, s[20:21]
	s_waitcnt lgkmcnt(8)
	s_barrier
	s_waitcnt lgkmcnt(0)


	v_mfma_f32_16x16x32_bf16 v[124:127], v[128:131], v[154:157], v[124:127]
	v_mfma_f32_16x16x32_bf16 v[120:123], v[136:139], v[154:157], v[120:123]
	v_mfma_f32_16x16x32_bf16 v[116:119], v[128:131], v[172:175], v[116:119]
	v_mfma_f32_16x16x32_bf16 v[104:107], v[136:139], v[172:175], v[104:107]
	v_mfma_f32_16x16x32_bf16 v[96:99], v[128:131], v[180:183], v[96:99]
	v_mfma_f32_16x16x32_bf16 v[88:91], v[136:139], v[180:183], v[88:91]
	v_mfma_f32_16x16x32_bf16 v[80:83], v[128:131], v[188:191], v[80:83]
	v_mfma_f32_16x16x32_bf16 v[72:75], v[136:139], v[188:191], v[72:75]
	v_mfma_f32_16x16x32_bf16 v[124:127], v[132:135], v[162:165], v[124:127]
	v_mfma_f32_16x16x32_bf16 v[120:123], v[150:153], v[162:165], v[120:123]
	v_mfma_f32_16x16x32_bf16 v[116:119], v[132:135], v[176:179], v[116:119]
	v_mfma_f32_16x16x32_bf16 v[104:107], v[150:153], v[176:179], v[104:107]
	v_mfma_f32_16x16x32_bf16 v[96:99], v[132:135], v[184:187], v[96:99]
	v_mfma_f32_16x16x32_bf16 v[88:91], v[150:153], v[184:187], v[88:91]
	v_mfma_f32_16x16x32_bf16 v[80:83], v[132:135], v[192:195], v[80:83]
	v_mfma_f32_16x16x32_bf16 v[72:75], v[150:153], v[192:195], v[72:75]

	s_barrier
	s_add_i32 s20, 0, 0x1c000
	s_add_i32 s21, s55, s25
	v_add_u32_e32 v144, s20, v158

	s_mov_b32 m0, s21
	ds_read_b128 v[196:199], v144
	ds_read_b128 v[200:203], v144 offset:1024
	ds_read_b128 v[204:207], v144 offset:2048
	ds_read_b128 v[212:215], v144 offset:3072
	global_load_lds_dwordx4 v140, s[66:67]
	s_add_i32 m0, s21, 0x2000
	s_nop 0

	global_load_lds_dwordx4 v142, s[66:67]
	s_barrier
	s_waitcnt lgkmcnt(0)


	v_mfma_f32_16x16x32_bf16 v[112:115], v[196:199], v[154:157], v[112:115]
	v_mfma_f32_16x16x32_bf16 v[108:111], v[204:207], v[154:157], v[108:111]
	v_mfma_f32_16x16x32_bf16 v[100:103], v[196:199], v[172:175], v[100:103]
	v_mfma_f32_16x16x32_bf16 v[92:95], v[204:207], v[172:175], v[92:95]
	v_mfma_f32_16x16x32_bf16 v[84:87], v[196:199], v[180:183], v[84:87]
	v_mfma_f32_16x16x32_bf16 v[76:79], v[204:207], v[180:183], v[76:79]
	v_mfma_f32_16x16x32_bf16 v[68:71], v[196:199], v[188:191], v[68:71]
	v_mfma_f32_16x16x32_bf16 v[64:67], v[204:207], v[188:191], v[64:67]
	v_mfma_f32_16x16x32_bf16 v[112:115], v[200:203], v[162:165], v[112:115]
	v_mfma_f32_16x16x32_bf16 v[108:111], v[212:215], v[162:165], v[108:111]
	v_mfma_f32_16x16x32_bf16 v[100:103], v[200:203], v[176:179], v[100:103]
	v_mfma_f32_16x16x32_bf16 v[92:95], v[212:215], v[176:179], v[92:95]
	v_mfma_f32_16x16x32_bf16 v[84:87], v[200:203], v[184:187], v[84:87]
	v_mfma_f32_16x16x32_bf16 v[76:79], v[212:215], v[184:187], v[76:79]
	v_mfma_f32_16x16x32_bf16 v[68:71], v[200:203], v[192:195], v[68:71]
	v_mfma_f32_16x16x32_bf16 v[64:67], v[212:215], v[192:195], v[64:67]

	s_mov_b32 m0, s33

	s_barrier
	ds_read_b128 v[154:157], v160 offset:49152
	ds_read_b128 v[162:165], v160 offset:50176
	ds_read_b128 v[172:175], v160 offset:51200
	ds_read_b128 v[176:179], v160 offset:52224
	ds_read_b128 v[180:183], v160 offset:53248
	ds_read_b128 v[184:187], v160 offset:54272
	ds_read_b128 v[188:191], v160 offset:55296
	ds_read_b128 v[192:195], v160 offset:56320
	global_load_lds_dwordx4 v140, s[68:69]
	s_mov_b32 m0, s34
	s_nop 0

	global_load_lds_dwordx4 v142, s[68:69]
	s_barrier
	s_waitcnt lgkmcnt(0)


	v_mfma_f32_16x16x32_bf16 v[60:63], v[128:131], v[154:157], v[60:63]
	v_mfma_f32_16x16x32_bf16 v[56:59], v[136:139], v[154:157], v[56:59]
	v_mfma_f32_16x16x32_bf16 v[52:55], v[128:131], v[172:175], v[52:55]
	v_mfma_f32_16x16x32_bf16 v[40:43], v[136:139], v[172:175], v[40:43]
	v_mfma_f32_16x16x32_bf16 v[36:39], v[128:131], v[180:183], v[36:39]
	v_mfma_f32_16x16x32_bf16 v[24:27], v[136:139], v[180:183], v[24:27]
	v_mfma_f32_16x16x32_bf16 v[20:23], v[128:131], v[188:191], v[20:23]
	v_mfma_f32_16x16x32_bf16 v[8:11], v[136:139], v[188:191], v[8:11]
	v_mfma_f32_16x16x32_bf16 v[60:63], v[132:135], v[162:165], v[60:63]
	v_mfma_f32_16x16x32_bf16 v[56:59], v[150:153], v[162:165], v[56:59]
	v_mfma_f32_16x16x32_bf16 v[52:55], v[132:135], v[176:179], v[52:55]
	v_mfma_f32_16x16x32_bf16 v[40:43], v[150:153], v[176:179], v[40:43]
	v_mfma_f32_16x16x32_bf16 v[36:39], v[132:135], v[184:187], v[36:39]
	v_mfma_f32_16x16x32_bf16 v[24:27], v[150:153], v[184:187], v[24:27]
	v_mfma_f32_16x16x32_bf16 v[20:23], v[132:135], v[192:195], v[20:23]
	v_mfma_f32_16x16x32_bf16 v[8:11], v[150:153], v[192:195], v[8:11]

	s_barrier
	s_add_u32 s18, s18, 0x160080
	s_addc_u32 s19, s19, 0
	s_add_i32 s20, s20, s25
	s_mov_b32 m0, s20
	s_nop 0

	global_load_lds_dwordx4 v140, s[18:19]
	s_add_i32 m0, s20, 0x2000
	s_nop 0

	global_load_lds_dwordx4 v142, s[18:19]
	s_waitcnt vmcnt(6)
	s_barrier

	v_mfma_f32_16x16x32_bf16 v[48:51], v[196:199], v[154:157], v[48:51]
	v_mfma_f32_16x16x32_bf16 v[44:47], v[204:207], v[154:157], v[44:47]
	v_mfma_f32_16x16x32_bf16 v[32:35], v[196:199], v[172:175], v[32:35]
	v_mfma_f32_16x16x32_bf16 v[28:31], v[204:207], v[172:175], v[28:31]
	v_mfma_f32_16x16x32_bf16 v[16:19], v[196:199], v[180:183], v[16:19]
	v_mfma_f32_16x16x32_bf16 v[12:15], v[204:207], v[180:183], v[12:15]
	v_mfma_f32_16x16x32_bf16 v[4:7], v[196:199], v[188:191], v[4:7]
	v_mfma_f32_16x16x32_bf16 v[0:3], v[204:207], v[188:191], v[0:3]
	v_mfma_f32_16x16x32_bf16 v[48:51], v[200:203], v[162:165], v[48:51]
	v_mfma_f32_16x16x32_bf16 v[44:47], v[212:215], v[162:165], v[44:47]
	v_mfma_f32_16x16x32_bf16 v[32:35], v[200:203], v[176:179], v[32:35]
	v_mfma_f32_16x16x32_bf16 v[28:31], v[212:215], v[176:179], v[28:31]
	v_mfma_f32_16x16x32_bf16 v[16:19], v[200:203], v[184:187], v[16:19]
	v_mfma_f32_16x16x32_bf16 v[12:15], v[212:215], v[184:187], v[12:15]
	v_mfma_f32_16x16x32_bf16 v[4:7], v[200:203], v[192:195], v[4:7]
	v_mfma_f32_16x16x32_bf16 v[0:3], v[212:215], v[192:195], v[0:3]

	s_add_u32 s16, s16, 0x100
	s_addc_u32 s17, s17, 0
	s_add_u32 s52, s52, 0x100
	s_addc_u32 s53, s53, 0
	s_cmp_ge_i32 s54, s51
	s_mov_b32 s18, s54
	s_barrier
	s_cbranch_scc0 .LBB0_1258
	v_mov_b32_e32 v128, v210
	v_mov_b32_e32 v129, v169
	s_mov_b64 s[16:17], -1
	v_lshl_add_u32 v128, v128, 4, v129
	v_ashrrev_i32_e32 v150, 2, v128
	v_and_b32_e32 v129, 3, v129
	v_and_b32_e32 v128, -4, v128
	v_lshl_add_u32 v162, v129, 6, v128
	s_cmp_lt_i32 s2, 0
	v_lshlrev_b32_e32 v144, 4, v129
	s_cbranch_scc0 .LBB0_1261
	s_lshl_b32 s13, s50, 8
	s_add_i32 s13, s13, s30
	v_add_u32_e32 v128, s13, v150
	v_ashrrev_i32_e32 v129, 31, v128
	v_readlane_b32 s52, v254, 22
	v_lshlrev_b64 v[128:129], 13, v[128:129]
	v_readlane_b32 s66, v254, 36
	v_readlane_b32 s67, v254, 37
	s_lshl_b32 s16, s49, 8
	s_ashr_i32 s17, s16, 31
	v_lshl_add_u64 v[128:129], s[66:67], 0, v[128:129]
	v_lshl_add_u64 v[128:129], s[16:17], 2, v[128:129]
	s_lshl_b32 s16, s31, 2
	s_mov_b32 s17, s3
	v_lshl_add_u64 v[128:129], v[128:129], 0, s[16:17]
	v_lshl_add_u64 v[152:153], v[128:129], 0, v[144:145]
	global_load_dwordx4 v[164:167], v[152:153], off
	global_load_dwordx4 v[172:175], v[152:153], off offset:64
	global_load_dwordx4 v[176:179], v[152:153], off offset:512
	global_load_dwordx4 v[180:183], v[152:153], off offset:576
	v_add_co_u32_e32 v136, vcc, s37, v152
	ds_bpermute_b32 v138, v162, v124
	s_nop 0
	v_addc_co_u32_e32 v137, vcc, 0, v153, vcc
	global_load_dwordx4 v[184:187], v[136:137], off
	global_load_dwordx4 v[188:191], v[136:137], off offset:64
	global_load_dwordx4 v[192:195], v[136:137], off offset:512
	global_load_dwordx4 v[132:135], v[136:137], off offset:576
	v_add_co_u32_e32 v208, vcc, s38, v152
	ds_bpermute_b32 v139, v162, v125
	s_nop 0
	v_addc_co_u32_e32 v209, vcc, 0, v153, vcc
	global_load_dwordx4 v[196:199], v[208:209], off
	global_load_dwordx4 v[200:203], v[208:209], off offset:64
	global_load_dwordx4 v[204:207], v[208:209], off offset:512
	global_load_dwordx4 v[212:215], v[208:209], off offset:576
	v_add_co_u32_e32 v154, vcc, s39, v152
	ds_bpermute_b32 v156, v162, v126
	s_nop 0
	v_addc_co_u32_e32 v155, vcc, 0, v153, vcc
	global_load_dwordx4 v[216:219], v[154:155], off
	global_load_dwordx4 v[220:223], v[154:155], off offset:64
	global_load_dwordx4 v[224:227], v[154:155], off offset:512
	global_load_dwordx4 v[128:131], v[154:155], off offset:576
	ds_bpermute_b32 v157, v162, v127
	ds_bpermute_b32 v228, v162, v120
	ds_bpermute_b32 v229, v162, v121
	ds_bpermute_b32 v230, v162, v122
	ds_bpermute_b32 v231, v162, v123
	ds_bpermute_b32 v232, v162, v112
	ds_bpermute_b32 v233, v162, v113
	ds_bpermute_b32 v234, v162, v114
	ds_bpermute_b32 v235, v162, v115
	ds_bpermute_b32 v236, v162, v108
	ds_bpermute_b32 v237, v162, v109
	ds_bpermute_b32 v238, v162, v110
	ds_bpermute_b32 v239, v162, v111
	ds_bpermute_b32 v240, v162, v116
	ds_bpermute_b32 v241, v162, v117
	ds_bpermute_b32 v242, v162, v118
	ds_bpermute_b32 v243, v162, v119
	ds_bpermute_b32 v244, v162, v104
	ds_bpermute_b32 v245, v162, v105
	ds_bpermute_b32 v246, v162, v106
	ds_bpermute_b32 v247, v162, v107
	ds_bpermute_b32 v248, v162, v100
	ds_bpermute_b32 v249, v162, v101
	ds_bpermute_b32 v250, v162, v102
	ds_bpermute_b32 v251, v162, v103
	ds_bpermute_b32 v252, v162, v94
	ds_bpermute_b32 v253, v162, v95
	v_readlane_b32 s53, v254, 23
	v_readlane_b32 s54, v254, 24
	v_readlane_b32 s55, v254, 25
	v_readlane_b32 s56, v254, 26
	v_readlane_b32 s57, v254, 27
	v_readlane_b32 s58, v254, 28
	v_readlane_b32 s59, v254, 29
	v_readlane_b32 s60, v254, 30
	v_readlane_b32 s61, v254, 31
	v_readlane_b32 s62, v254, 32
	v_readlane_b32 s63, v254, 33
	v_readlane_b32 s64, v254, 34
	v_readlane_b32 s65, v254, 35
	s_mov_b64 s[16:17], 0
	s_waitcnt vmcnt(0) lgkmcnt(0)
	v_pk_add_f32 v[164:165], v[164:165], v[138:139]
	ds_bpermute_b32 v138, v162, v92
	ds_bpermute_b32 v139, v162, v93
	v_pk_add_f32 v[166:167], v[166:167], v[156:157]
	v_pk_add_f32 v[172:173], v[172:173], v[228:229]
	v_pk_add_f32 v[174:175], v[174:175], v[230:231]
	v_pk_add_f32 v[178:179], v[178:179], v[234:235]
	v_pk_add_f32 v[176:177], v[176:177], v[232:233]
	v_pk_add_f32 v[182:183], v[182:183], v[238:239]
	v_pk_add_f32 v[180:181], v[180:181], v[236:237]
	global_store_dwordx4 v[152:153], v[164:167], off
	global_store_dwordx4 v[152:153], v[172:175], off offset:64
	global_store_dwordx4 v[152:153], v[176:179], off offset:512
	global_store_dwordx4 v[152:153], v[180:183], off offset:576
	v_pk_add_f32 v[166:167], v[186:187], v[242:243]
	v_pk_add_f32 v[164:165], v[184:185], v[240:241]
	v_pk_add_f32 v[172:173], v[188:189], v[244:245]
	v_add_co_u32_e32 v156, vcc, s40, v152
	v_pk_add_f32 v[174:175], v[190:191], v[246:247]
	v_pk_add_f32 v[178:179], v[194:195], v[250:251]
	v_pk_add_f32 v[176:177], v[192:193], v[248:249]
	global_store_dwordx4 v[136:137], v[164:167], off
	global_store_dwordx4 v[136:137], v[172:175], off offset:64
	global_store_dwordx4 v[136:137], v[176:179], off offset:512
	v_addc_co_u32_e32 v157, vcc, 0, v153, vcc
	ds_bpermute_b32 v172, v162, v98
	ds_bpermute_b32 v173, v162, v99
	v_pk_add_f32 v[134:135], v[134:135], v[252:253]
	global_load_dwordx4 v[164:167], v[156:157], off
	s_waitcnt lgkmcnt(2)
	v_pk_add_f32 v[132:133], v[132:133], v[138:139]
	global_store_dwordx4 v[136:137], v[132:135], off offset:576
	ds_bpermute_b32 v132, v162, v96
	ds_bpermute_b32 v133, v162, v97
	ds_bpermute_b32 v136, v162, v90
	ds_bpermute_b32 v137, v162, v91
	ds_bpermute_b32 v138, v162, v88
	ds_bpermute_b32 v139, v162, v89
	s_waitcnt lgkmcnt(6)
	v_pk_add_f32 v[134:135], v[198:199], v[172:173]
	global_load_dwordx4 v[172:175], v[156:157], off offset:64
	s_waitcnt lgkmcnt(4)
	v_pk_add_f32 v[132:133], v[196:197], v[132:133]
	global_store_dwordx4 v[208:209], v[132:135], off
	ds_bpermute_b32 v180, v162, v76
	ds_bpermute_b32 v182, v162, v78
	s_waitcnt lgkmcnt(4)
	v_pk_add_f32 v[134:135], v[202:203], v[136:137]
	ds_bpermute_b32 v136, v162, v86
	ds_bpermute_b32 v137, v162, v87
	s_waitcnt lgkmcnt(4)
	v_pk_add_f32 v[132:133], v[200:201], v[138:139]
	ds_bpermute_b32 v138, v162, v84
	ds_bpermute_b32 v139, v162, v85
	global_store_dwordx4 v[208:209], v[132:135], off offset:64
	global_load_dwordx4 v[132:135], v[156:157], off offset:512
	s_waitcnt lgkmcnt(2)
	v_pk_add_f32 v[178:179], v[206:207], v[136:137]
	ds_bpermute_b32 v183, v162, v79
	s_waitcnt lgkmcnt(1)
	v_pk_add_f32 v[176:177], v[204:205], v[138:139]
	global_load_dwordx4 v[136:139], v[156:157], off offset:576
	ds_bpermute_b32 v181, v162, v77
	global_store_dwordx4 v[208:209], v[176:179], off offset:512
	v_add_co_u32_e32 v204, vcc, s41, v152
	s_waitcnt lgkmcnt(1)
	v_pk_add_f32 v[178:179], v[214:215], v[182:183]
	s_waitcnt lgkmcnt(0)
	v_pk_add_f32 v[176:177], v[212:213], v[180:181]
	ds_bpermute_b32 v180, v162, v80
	ds_bpermute_b32 v181, v162, v81
	ds_bpermute_b32 v182, v162, v82
	ds_bpermute_b32 v183, v162, v83
	v_addc_co_u32_e32 v205, vcc, 0, v153, vcc
	global_store_dwordx4 v[208:209], v[176:179], off offset:576
	global_load_dwordx4 v[176:179], v[204:205], off
	s_waitcnt lgkmcnt(0)
	v_pk_add_f32 v[182:183], v[218:219], v[182:183]
	global_load_dwordx4 v[184:187], v[204:205], off offset:64
	v_pk_add_f32 v[180:181], v[216:217], v[180:181]
	ds_bpermute_b32 v188, v162, v74
	ds_bpermute_b32 v189, v162, v75
	global_store_dwordx4 v[154:155], v[180:183], off
	ds_bpermute_b32 v180, v162, v72
	ds_bpermute_b32 v181, v162, v73
	ds_bpermute_b32 v192, v162, v68
	s_waitcnt lgkmcnt(3)
	v_pk_add_f32 v[182:183], v[222:223], v[188:189]
	global_load_dwordx4 v[188:191], v[204:205], off offset:512
	ds_bpermute_b32 v193, v162, v69
	s_waitcnt lgkmcnt(2)
	v_pk_add_f32 v[180:181], v[220:221], v[180:181]
	ds_bpermute_b32 v194, v162, v70
	ds_bpermute_b32 v195, v162, v71
	global_store_dwordx4 v[154:155], v[180:183], off offset:64
	global_load_dwordx4 v[180:183], v[204:205], off offset:576
	ds_bpermute_b32 v200, v162, v64
	ds_bpermute_b32 v196, v162, v66
	ds_bpermute_b32 v197, v162, v67
	ds_bpermute_b32 v201, v162, v65
	v_add_co_u32_e32 v206, vcc, s42, v152
	s_waitcnt lgkmcnt(4)
	v_pk_add_f32 v[194:195], v[226:227], v[194:195]
	v_pk_add_f32 v[192:193], v[224:225], v[192:193]
	v_addc_co_u32_e32 v207, vcc, 0, v153, vcc
	global_store_dwordx4 v[154:155], v[192:195], off offset:512
	global_load_dwordx4 v[192:195], v[206:207], off
	s_waitcnt lgkmcnt(1)
	v_pk_add_f32 v[130:131], v[130:131], v[196:197]
	s_waitcnt lgkmcnt(0)
	v_pk_add_f32 v[128:129], v[128:129], v[200:201]
	global_load_dwordx4 v[196:199], v[206:207], off offset:64
	ds_bpermute_b32 v202, v162, v62
	ds_bpermute_b32 v203, v162, v63
	global_store_dwordx4 v[154:155], v[128:131], off offset:576
	ds_bpermute_b32 v128, v162, v60
	ds_bpermute_b32 v129, v162, v61
	ds_bpermute_b32 v208, v162, v58
	ds_bpermute_b32 v209, v162, v59
	s_waitcnt vmcnt(18) lgkmcnt(4)
	v_pk_add_f32 v[130:131], v[166:167], v[202:203]
	ds_bpermute_b32 v154, v162, v56
	global_load_dwordx4 v[200:203], v[206:207], off offset:512
	ds_bpermute_b32 v155, v162, v57
	s_waitcnt lgkmcnt(4)
	v_pk_add_f32 v[128:129], v[164:165], v[128:129]
	global_load_dwordx4 v[164:167], v[206:207], off offset:576
	ds_bpermute_b32 v212, v162, v44
	global_store_dwordx4 v[156:157], v[128:131], off
	ds_bpermute_b32 v214, v162, v46
	ds_bpermute_b32 v215, v162, v47
	s_waitcnt vmcnt(19) lgkmcnt(5)
	v_pk_add_f32 v[130:131], v[174:175], v[208:209]
	v_add_co_u32_e32 v208, vcc, s43, v152
	s_waitcnt lgkmcnt(3)
	v_pk_add_f32 v[128:129], v[172:173], v[154:155]
	v_addc_co_u32_e32 v209, vcc, 0, v153, vcc
	global_store_dwordx4 v[156:157], v[128:131], off offset:64
	ds_bpermute_b32 v172, v162, v48
	ds_bpermute_b32 v173, v162, v49
	global_load_dwordx4 v[128:131], v[208:209], off
	global_load_dwordx4 v[152:155], v[208:209], off offset:64
	ds_bpermute_b32 v174, v162, v50
	ds_bpermute_b32 v175, v162, v51
	ds_bpermute_b32 v213, v162, v45
	s_waitcnt vmcnt(19) lgkmcnt(3)
	v_pk_add_f32 v[132:133], v[132:133], v[172:173]
	ds_bpermute_b32 v172, v162, v54
	ds_bpermute_b32 v173, v162, v55
	s_waitcnt lgkmcnt(3)
	v_pk_add_f32 v[134:135], v[134:135], v[174:175]
	global_store_dwordx4 v[156:157], v[132:135], off offset:512
	s_waitcnt vmcnt(16) lgkmcnt(0)
	v_pk_add_f32 v[174:175], v[178:179], v[172:173]
	v_pk_add_f32 v[134:135], v[138:139], v[214:215]
	v_pk_add_f32 v[132:133], v[136:137], v[212:213]
	global_store_dwordx4 v[156:157], v[132:135], off offset:576
	global_load_dwordx4 v[132:135], v[208:209], off offset:512
	ds_bpermute_b32 v156, v162, v52
	global_load_dwordx4 v[136:139], v[208:209], off offset:576
	ds_bpermute_b32 v157, v162, v53
	ds_bpermute_b32 v212, v162, v40
	ds_bpermute_b32 v214, v162, v42
	ds_bpermute_b32 v215, v162, v43
	ds_bpermute_b32 v213, v162, v41
	s_waitcnt lgkmcnt(4)
	v_pk_add_f32 v[172:173], v[176:177], v[156:157]
	global_store_dwordx4 v[204:205], v[172:175], off
	ds_bpermute_b32 v156, v162, v32
	ds_bpermute_b32 v157, v162, v33
	s_waitcnt vmcnt(19) lgkmcnt(3)
	v_pk_add_f32 v[174:175], v[186:187], v[214:215]
	s_waitcnt lgkmcnt(2)
	v_pk_add_f32 v[172:173], v[184:185], v[212:213]
	global_store_dwordx4 v[204:205], v[172:175], off offset:64
	ds_bpermute_b32 v172, v162, v34
	ds_bpermute_b32 v173, v162, v35
	ds_bpermute_b32 v176, v162, v28
	ds_bpermute_b32 v178, v162, v30
	ds_bpermute_b32 v179, v162, v31
	ds_bpermute_b32 v177, v162, v29
	s_waitcnt vmcnt(18) lgkmcnt(4)
	v_pk_add_f32 v[174:175], v[190:191], v[172:173]
	v_pk_add_f32 v[172:173], v[188:189], v[156:157]
	global_store_dwordx4 v[204:205], v[172:175], off offset:512
	ds_bpermute_b32 v156, v162, v36
	ds_bpermute_b32 v157, v162, v37
	s_waitcnt vmcnt(17) lgkmcnt(3)
	v_pk_add_f32 v[174:175], v[182:183], v[178:179]
	s_waitcnt lgkmcnt(2)
	v_pk_add_f32 v[172:173], v[180:181], v[176:177]
	global_store_dwordx4 v[204:205], v[172:175], off offset:576
	ds_bpermute_b32 v172, v162, v38
	ds_bpermute_b32 v173, v162, v39
	ds_bpermute_b32 v176, v162, v24
	ds_bpermute_b32 v178, v162, v26
	ds_bpermute_b32 v179, v162, v27
	ds_bpermute_b32 v177, v162, v25
	s_waitcnt vmcnt(16) lgkmcnt(4)
	v_pk_add_f32 v[174:175], v[194:195], v[172:173]
	v_pk_add_f32 v[172:173], v[192:193], v[156:157]
	global_store_dwordx4 v[206:207], v[172:175], off
	ds_bpermute_b32 v156, v162, v16
	ds_bpermute_b32 v157, v162, v17
	s_waitcnt vmcnt(16) lgkmcnt(3)
	v_pk_add_f32 v[174:175], v[198:199], v[178:179]
	s_waitcnt lgkmcnt(2)
	v_pk_add_f32 v[172:173], v[196:197], v[176:177]
	ds_bpermute_b32 v176, v162, v12
	ds_bpermute_b32 v178, v162, v14
	ds_bpermute_b32 v179, v162, v15
	ds_bpermute_b32 v177, v162, v13
	global_store_dwordx4 v[206:207], v[172:175], off offset:64
	ds_bpermute_b32 v172, v162, v18
	ds_bpermute_b32 v173, v162, v19
	s_waitcnt vmcnt(14) lgkmcnt(3)
	v_pk_add_f32 v[166:167], v[166:167], v[178:179]
	s_waitcnt lgkmcnt(2)
	v_pk_add_f32 v[164:165], v[164:165], v[176:177]
	global_store_dwordx4 v[206:207], v[164:167], off offset:576
	ds_bpermute_b32 v164, v162, v22
	s_waitcnt lgkmcnt(1)
	v_pk_add_f32 v[174:175], v[202:203], v[172:173]
	v_pk_add_f32 v[172:173], v[200:201], v[156:157]
	ds_bpermute_b32 v156, v162, v20
	ds_bpermute_b32 v157, v162, v21
	ds_bpermute_b32 v165, v162, v23
	global_store_dwordx4 v[206:207], v[172:175], off offset:512
	ds_bpermute_b32 v166, v162, v8
	ds_bpermute_b32 v172, v162, v10
	ds_bpermute_b32 v173, v162, v11
	ds_bpermute_b32 v167, v162, v9
	s_waitcnt vmcnt(13) lgkmcnt(4)
	v_pk_add_f32 v[130:131], v[130:131], v[164:165]
	v_pk_add_f32 v[128:129], v[128:129], v[156:157]
	global_store_dwordx4 v[208:209], v[128:131], off
	s_waitcnt vmcnt(13) lgkmcnt(1)
	s_nop 0
	v_pk_add_f32 v[130:131], v[154:155], v[172:173]
	s_waitcnt lgkmcnt(0)
	v_pk_add_f32 v[128:129], v[152:153], v[166:167]
	global_store_dwordx4 v[208:209], v[128:131], off offset:64
	ds_bpermute_b32 v128, v162, v4
	ds_bpermute_b32 v129, v162, v5
	ds_bpermute_b32 v130, v162, v6
	ds_bpermute_b32 v131, v162, v7
	ds_bpermute_b32 v152, v162, v0
	ds_bpermute_b32 v154, v162, v2
	ds_bpermute_b32 v155, v162, v3
	ds_bpermute_b32 v153, v162, v1
	s_waitcnt vmcnt(11) lgkmcnt(4)
	v_pk_add_f32 v[130:131], v[134:135], v[130:131]
	v_pk_add_f32 v[128:129], v[132:133], v[128:129]
	global_store_dwordx4 v[208:209], v[128:131], off offset:512
	s_waitcnt vmcnt(11) lgkmcnt(1)
	s_nop 0
	v_pk_add_f32 v[130:131], v[138:139], v[154:155]
	s_waitcnt lgkmcnt(0)
	v_pk_add_f32 v[128:129], v[136:137], v[152:153]
	global_store_dwordx4 v[208:209], v[128:131], off offset:576
